# residual epilogue stores tagged device-scope so the grid barrier's L2 write-back has less to flush
# speedup vs baseline: 1.0082x; 1.0082x over previous
;     ...
; #pragma unroll
;     for (int ai = 0; ai < 2; ++ai)
; #pragma unroll
;       for (int m = 0; m < 4; ++m)
;         epi(brow + ai * HALF + wr * 64 + m * 16 + fr, bcol + wc * 32, fq, acc[ai][0][m][0], acc[ai][0][m][1], acc[ai][1][m][0], acc[ai][1][m][1]);
.LBB0_1463:
	v_or_b32_e32 v0, s10, v218
	v_add_u32_e32 v136, v0, v215
	v_ashrrev_i32_e32 v137, 31, v136
	v_readlane_b32 s6, v253, 60
	v_lshl_or_b32 v0, v139, 5, s90
	v_lshlrev_b64 v[132:133], 12, v[136:137]
	v_readlane_b32 s7, v253, 61
	v_lshlrev_b64 v[134:135], 2, v[0:1]
	v_mov_b32_e32 v131, v1
	v_lshl_add_u64 v[132:133], s[6:7], 0, v[132:133]
	v_lshl_add_u64 v[132:133], v[132:133], 0, v[134:135]
	v_lshl_add_u64 v[132:133], v[132:133], 0, v[130:131]
	v_cndmask_b32_e64 v0, 0, 1, s[4:5]
	v_and_b32_e32 v134, 1, v210
	v_cmp_eq_u32_e32 vcc, 0, v134
	s_nop 1
	v_mov_b32_e32 v135, 0xfffff040
	v_cndmask_b32_e32 v134, v135, v1, vcc
	v_cndmask_b32_e32 v135, -1, v1, vcc
	v_lshl_add_u64 v[132:133], v[132:133], 0, v[134:135]
	s_mov_b64 s[6:7], 0x1000
	v_lshl_add_u64 v[136:137], v[132:133], 0, s[6:7]
	v_mov_b64_e32 v[138:139], v[132:133]
	v_mov_b64_e32 v[140:141], v[136:137]
	global_load_dwordx4 v[168:171], v[138:139], off
	global_load_dwordx4 v[172:175], v[140:141], off
	global_load_dwordx4 v[176:179], v[138:139], off offset:512
	global_load_dwordx4 v[180:183], v[140:141], off offset:512
	s_mov_b64 s[6:7], 0x10000
	v_lshl_add_u64 v[142:143], v[132:133], 0, s[6:7]
	v_lshl_add_u64 v[144:145], v[136:137], 0, s[6:7]
	global_load_dwordx4 v[184:187], v[142:143], off
	global_load_dwordx4 v[188:191], v[144:145], off
	global_load_dwordx4 v[192:195], v[142:143], off offset:512
	global_load_dwordx4 v[196:199], v[144:145], off offset:512
	s_mov_b64 s[6:7], 0x20000
	v_lshl_add_u64 v[146:147], v[132:133], 0, s[6:7]
	v_lshl_add_u64 v[148:149], v[136:137], 0, s[6:7]
	global_load_dwordx4 v[220:223], v[146:147], off
	global_load_dwordx4 v[224:227], v[148:149], off
	global_load_dwordx4 v[228:231], v[146:147], off offset:512
	global_load_dwordx4 v[232:235], v[148:149], off offset:512
	s_mov_b64 s[6:7], 0x30000
	v_lshl_add_u64 v[150:151], v[132:133], 0, s[6:7]
	v_lshl_add_u64 v[152:153], v[136:137], 0, s[6:7]
	global_load_dwordx4 v[236:239], v[150:151], off
	global_load_dwordx4 v[240:243], v[152:153], off
	global_load_dwordx4 v[244:247], v[150:151], off offset:512
	global_load_dwordx4 v[248:251], v[152:153], off offset:512
	v_mov_b32_dpp v200, v118 quad_perm:[1,0,3,2] row_mask:0xf bank_mask:0xf
	v_cndmask_b32_dpp v201, v114, v200, vcc quad_perm:[1,0,3,2] row_mask:0xf bank_mask:0xf
	v_cndmask_b32_e32 v118, v201, v118, vcc
	v_cndmask_b32_e32 v114, v114, v201, vcc
	v_mov_b32_dpp v200, v119 quad_perm:[1,0,3,2] row_mask:0xf bank_mask:0xf
	v_cndmask_b32_dpp v201, v115, v200, vcc quad_perm:[1,0,3,2] row_mask:0xf bank_mask:0xf
	v_cndmask_b32_e32 v119, v201, v119, vcc
	v_cndmask_b32_e32 v115, v115, v201, vcc
	v_mov_b32_dpp v200, v120 quad_perm:[1,0,3,2] row_mask:0xf bank_mask:0xf
	v_cndmask_b32_dpp v201, v116, v200, vcc quad_perm:[1,0,3,2] row_mask:0xf bank_mask:0xf
	v_cndmask_b32_e32 v120, v201, v120, vcc
	v_cndmask_b32_e32 v116, v116, v201, vcc
	v_mov_b32_dpp v200, v121 quad_perm:[1,0,3,2] row_mask:0xf bank_mask:0xf
	v_cndmask_b32_dpp v201, v117, v200, vcc quad_perm:[1,0,3,2] row_mask:0xf bank_mask:0xf
	v_cndmask_b32_e32 v121, v201, v121, vcc
	v_cndmask_b32_e32 v117, v117, v201, vcc
	v_mov_b32_dpp v200, v126 quad_perm:[1,0,3,2] row_mask:0xf bank_mask:0xf
	v_cndmask_b32_dpp v201, v122, v200, vcc quad_perm:[1,0,3,2] row_mask:0xf bank_mask:0xf
	v_cndmask_b32_e32 v126, v201, v126, vcc
	v_cndmask_b32_e32 v122, v122, v201, vcc
	v_mov_b32_dpp v200, v127 quad_perm:[1,0,3,2] row_mask:0xf bank_mask:0xf
	v_cndmask_b32_dpp v201, v123, v200, vcc quad_perm:[1,0,3,2] row_mask:0xf bank_mask:0xf
	v_cndmask_b32_e32 v127, v201, v127, vcc
	v_cndmask_b32_e32 v123, v123, v201, vcc
	v_mov_b32_dpp v200, v128 quad_perm:[1,0,3,2] row_mask:0xf bank_mask:0xf
	v_cndmask_b32_dpp v201, v124, v200, vcc quad_perm:[1,0,3,2] row_mask:0xf bank_mask:0xf
	v_cndmask_b32_e32 v128, v201, v128, vcc
	v_cndmask_b32_e32 v124, v124, v201, vcc
	v_mov_b32_dpp v200, v129 quad_perm:[1,0,3,2] row_mask:0xf bank_mask:0xf
	v_cndmask_b32_dpp v201, v125, v200, vcc quad_perm:[1,0,3,2] row_mask:0xf bank_mask:0xf
	v_cndmask_b32_e32 v129, v201, v129, vcc
	v_cndmask_b32_e32 v125, v125, v201, vcc
	s_waitcnt vmcnt(12)
	v_pk_add_f32 v[168:169], v[118:119], v[168:169]
	v_pk_add_f32 v[170:171], v[120:121], v[170:171]
	v_pk_add_f32 v[172:173], v[114:115], v[172:173]
	v_pk_add_f32 v[174:175], v[116:117], v[174:175]
	v_pk_add_f32 v[176:177], v[126:127], v[176:177]
	v_pk_add_f32 v[178:179], v[128:129], v[178:179]
	v_pk_add_f32 v[180:181], v[122:123], v[180:181]
	v_pk_add_f32 v[182:183], v[124:125], v[182:183]
	global_store_dwordx4 v[138:139], v[168:171], off sc1
	global_store_dwordx4 v[140:141], v[172:175], off sc1
	global_store_dwordx4 v[138:139], v[176:179], off offset:512 sc1
	global_store_dwordx4 v[140:141], v[180:183], off offset:512 sc1
	s_nop 1
	s_mov_b64 s[6:7], 0x80000
	v_lshl_add_u64 v[138:139], v[132:133], 0, s[6:7]
	v_lshl_add_u64 v[140:141], v[136:137], 0, s[6:7]
	global_load_dwordx4 v[168:171], v[138:139], off
	global_load_dwordx4 v[172:175], v[140:141], off
	global_load_dwordx4 v[176:179], v[138:139], off offset:512
	global_load_dwordx4 v[180:183], v[140:141], off offset:512
	v_mov_b32_dpp v200, v102 quad_perm:[1,0,3,2] row_mask:0xf bank_mask:0xf
	v_cndmask_b32_dpp v201, v98, v200, vcc quad_perm:[1,0,3,2] row_mask:0xf bank_mask:0xf
	v_cndmask_b32_e32 v102, v201, v102, vcc
	v_cndmask_b32_e32 v98, v98, v201, vcc
	v_mov_b32_dpp v200, v103 quad_perm:[1,0,3,2] row_mask:0xf bank_mask:0xf
	v_cndmask_b32_dpp v201, v99, v200, vcc quad_perm:[1,0,3,2] row_mask:0xf bank_mask:0xf
	v_cndmask_b32_e32 v103, v201, v103, vcc
	v_cndmask_b32_e32 v99, v99, v201, vcc
	v_mov_b32_dpp v200, v104 quad_perm:[1,0,3,2] row_mask:0xf bank_mask:0xf
	v_cndmask_b32_dpp v201, v100, v200, vcc quad_perm:[1,0,3,2] row_mask:0xf bank_mask:0xf
	v_cndmask_b32_e32 v104, v201, v104, vcc
	v_cndmask_b32_e32 v100, v100, v201, vcc
	v_mov_b32_dpp v200, v105 quad_perm:[1,0,3,2] row_mask:0xf bank_mask:0xf
	v_cndmask_b32_dpp v201, v101, v200, vcc quad_perm:[1,0,3,2] row_mask:0xf bank_mask:0xf
	v_cndmask_b32_e32 v105, v201, v105, vcc
	v_cndmask_b32_e32 v101, v101, v201, vcc
	v_mov_b32_dpp v200, v110 quad_perm:[1,0,3,2] row_mask:0xf bank_mask:0xf
	v_cndmask_b32_dpp v201, v106, v200, vcc quad_perm:[1,0,3,2] row_mask:0xf bank_mask:0xf
	v_cndmask_b32_e32 v110, v201, v110, vcc
	v_cndmask_b32_e32 v106, v106, v201, vcc
	v_mov_b32_dpp v200, v111 quad_perm:[1,0,3,2] row_mask:0xf bank_mask:0xf
	v_cndmask_b32_dpp v201, v107, v200, vcc quad_perm:[1,0,3,2] row_mask:0xf bank_mask:0xf
	v_cndmask_b32_e32 v111, v201, v111, vcc
	v_cndmask_b32_e32 v107, v107, v201, vcc
	v_mov_b32_dpp v200, v112 quad_perm:[1,0,3,2] row_mask:0xf bank_mask:0xf
	v_cndmask_b32_dpp v201, v108, v200, vcc quad_perm:[1,0,3,2] row_mask:0xf bank_mask:0xf
	v_cndmask_b32_e32 v112, v201, v112, vcc
	v_cndmask_b32_e32 v108, v108, v201, vcc
	v_mov_b32_dpp v200, v113 quad_perm:[1,0,3,2] row_mask:0xf bank_mask:0xf
	v_cndmask_b32_dpp v201, v109, v200, vcc quad_perm:[1,0,3,2] row_mask:0xf bank_mask:0xf
	v_cndmask_b32_e32 v113, v201, v113, vcc
	v_cndmask_b32_e32 v109, v109, v201, vcc
	s_waitcnt vmcnt(16)
;     ...
; #pragma unroll
;     for (int ai = 0; ai < 2; ++ai)
; #pragma unroll
;       for (int m = 0; m < 4; ++m)
;         epi(brow + ai * HALF + wr * 64 + m * 16 + fr, bcol + wc * 32, fq, acc[ai][0][m][0], acc[ai][0][m][1], acc[ai][1][m][0], acc[ai][1][m][1]);
	v_pk_add_f32 v[184:185], v[102:103], v[184:185]
	v_pk_add_f32 v[186:187], v[104:105], v[186:187]
	v_pk_add_f32 v[188:189], v[98:99], v[188:189]
	v_pk_add_f32 v[190:191], v[100:101], v[190:191]
	v_pk_add_f32 v[192:193], v[110:111], v[192:193]
	v_pk_add_f32 v[194:195], v[112:113], v[194:195]
	v_pk_add_f32 v[196:197], v[106:107], v[196:197]
	v_pk_add_f32 v[198:199], v[108:109], v[198:199]
	global_store_dwordx4 v[142:143], v[184:187], off sc1
	global_store_dwordx4 v[144:145], v[188:191], off sc1
	global_store_dwordx4 v[142:143], v[192:195], off offset:512 sc1
	global_store_dwordx4 v[144:145], v[196:199], off offset:512 sc1
	s_nop 1
	s_mov_b64 s[6:7], 0x90000
	v_lshl_add_u64 v[142:143], v[132:133], 0, s[6:7]
	v_lshl_add_u64 v[144:145], v[136:137], 0, s[6:7]
	global_load_dwordx4 v[184:187], v[142:143], off
	global_load_dwordx4 v[188:191], v[144:145], off
	global_load_dwordx4 v[192:195], v[142:143], off offset:512
	global_load_dwordx4 v[196:199], v[144:145], off offset:512
	v_mov_b32_dpp v200, v86 quad_perm:[1,0,3,2] row_mask:0xf bank_mask:0xf
	v_cndmask_b32_dpp v201, v82, v200, vcc quad_perm:[1,0,3,2] row_mask:0xf bank_mask:0xf
	v_cndmask_b32_e32 v86, v201, v86, vcc
	v_cndmask_b32_e32 v82, v82, v201, vcc
	v_mov_b32_dpp v200, v87 quad_perm:[1,0,3,2] row_mask:0xf bank_mask:0xf
	v_cndmask_b32_dpp v201, v83, v200, vcc quad_perm:[1,0,3,2] row_mask:0xf bank_mask:0xf
	v_cndmask_b32_e32 v87, v201, v87, vcc
	v_cndmask_b32_e32 v83, v83, v201, vcc
	v_mov_b32_dpp v200, v88 quad_perm:[1,0,3,2] row_mask:0xf bank_mask:0xf
	v_cndmask_b32_dpp v201, v84, v200, vcc quad_perm:[1,0,3,2] row_mask:0xf bank_mask:0xf
	v_cndmask_b32_e32 v88, v201, v88, vcc
	v_cndmask_b32_e32 v84, v84, v201, vcc
	v_mov_b32_dpp v200, v89 quad_perm:[1,0,3,2] row_mask:0xf bank_mask:0xf
	v_cndmask_b32_dpp v201, v85, v200, vcc quad_perm:[1,0,3,2] row_mask:0xf bank_mask:0xf
	v_cndmask_b32_e32 v89, v201, v89, vcc
	v_cndmask_b32_e32 v85, v85, v201, vcc
	v_mov_b32_dpp v200, v94 quad_perm:[1,0,3,2] row_mask:0xf bank_mask:0xf
	v_cndmask_b32_dpp v201, v90, v200, vcc quad_perm:[1,0,3,2] row_mask:0xf bank_mask:0xf
	v_cndmask_b32_e32 v94, v201, v94, vcc
	v_cndmask_b32_e32 v90, v90, v201, vcc
	v_mov_b32_dpp v200, v95 quad_perm:[1,0,3,2] row_mask:0xf bank_mask:0xf
	v_cndmask_b32_dpp v201, v91, v200, vcc quad_perm:[1,0,3,2] row_mask:0xf bank_mask:0xf
	v_cndmask_b32_e32 v95, v201, v95, vcc
	v_cndmask_b32_e32 v91, v91, v201, vcc
	v_mov_b32_dpp v200, v96 quad_perm:[1,0,3,2] row_mask:0xf bank_mask:0xf
	v_cndmask_b32_dpp v201, v92, v200, vcc quad_perm:[1,0,3,2] row_mask:0xf bank_mask:0xf
	v_cndmask_b32_e32 v96, v201, v96, vcc
	v_cndmask_b32_e32 v92, v92, v201, vcc
	v_mov_b32_dpp v200, v97 quad_perm:[1,0,3,2] row_mask:0xf bank_mask:0xf
	v_cndmask_b32_dpp v201, v93, v200, vcc quad_perm:[1,0,3,2] row_mask:0xf bank_mask:0xf
	v_cndmask_b32_e32 v97, v201, v97, vcc
	v_cndmask_b32_e32 v93, v93, v201, vcc
	s_waitcnt vmcnt(20)
	v_pk_add_f32 v[220:221], v[86:87], v[220:221]
	v_pk_add_f32 v[222:223], v[88:89], v[222:223]
	v_pk_add_f32 v[224:225], v[82:83], v[224:225]
	v_pk_add_f32 v[226:227], v[84:85], v[226:227]
	v_pk_add_f32 v[228:229], v[94:95], v[228:229]
	v_pk_add_f32 v[230:231], v[96:97], v[230:231]
	v_pk_add_f32 v[232:233], v[90:91], v[232:233]
	v_pk_add_f32 v[234:235], v[92:93], v[234:235]
	global_store_dwordx4 v[146:147], v[220:223], off sc1
	global_store_dwordx4 v[148:149], v[224:227], off sc1
	global_store_dwordx4 v[146:147], v[228:231], off offset:512 sc1
	global_store_dwordx4 v[148:149], v[232:235], off offset:512 sc1
	s_nop 1
	s_mov_b64 s[6:7], 0xa0000
	v_lshl_add_u64 v[146:147], v[132:133], 0, s[6:7]
	v_lshl_add_u64 v[148:149], v[136:137], 0, s[6:7]
	global_load_dwordx4 v[220:223], v[146:147], off
	global_load_dwordx4 v[224:227], v[148:149], off
	global_load_dwordx4 v[228:231], v[146:147], off offset:512
	global_load_dwordx4 v[232:235], v[148:149], off offset:512
	v_mov_b32_dpp v200, v70 quad_perm:[1,0,3,2] row_mask:0xf bank_mask:0xf
	v_cndmask_b32_dpp v201, v66, v200, vcc quad_perm:[1,0,3,2] row_mask:0xf bank_mask:0xf
	v_cndmask_b32_e32 v70, v201, v70, vcc
	v_cndmask_b32_e32 v66, v66, v201, vcc
	v_mov_b32_dpp v200, v71 quad_perm:[1,0,3,2] row_mask:0xf bank_mask:0xf
	v_cndmask_b32_dpp v201, v67, v200, vcc quad_perm:[1,0,3,2] row_mask:0xf bank_mask:0xf
	v_cndmask_b32_e32 v71, v201, v71, vcc
	v_cndmask_b32_e32 v67, v67, v201, vcc
	v_mov_b32_dpp v200, v72 quad_perm:[1,0,3,2] row_mask:0xf bank_mask:0xf
	v_cndmask_b32_dpp v201, v68, v200, vcc quad_perm:[1,0,3,2] row_mask:0xf bank_mask:0xf
	v_cndmask_b32_e32 v72, v201, v72, vcc
	v_cndmask_b32_e32 v68, v68, v201, vcc
	v_mov_b32_dpp v200, v73 quad_perm:[1,0,3,2] row_mask:0xf bank_mask:0xf
	v_cndmask_b32_dpp v201, v69, v200, vcc quad_perm:[1,0,3,2] row_mask:0xf bank_mask:0xf
	v_cndmask_b32_e32 v73, v201, v73, vcc
	v_cndmask_b32_e32 v69, v69, v201, vcc
	v_mov_b32_dpp v200, v78 quad_perm:[1,0,3,2] row_mask:0xf bank_mask:0xf
	v_cndmask_b32_dpp v201, v74, v200, vcc quad_perm:[1,0,3,2] row_mask:0xf bank_mask:0xf
	v_cndmask_b32_e32 v78, v201, v78, vcc
	v_cndmask_b32_e32 v74, v74, v201, vcc
	v_mov_b32_dpp v200, v79 quad_perm:[1,0,3,2] row_mask:0xf bank_mask:0xf
	v_cndmask_b32_dpp v201, v75, v200, vcc quad_perm:[1,0,3,2] row_mask:0xf bank_mask:0xf
	v_cndmask_b32_e32 v79, v201, v79, vcc
	v_cndmask_b32_e32 v75, v75, v201, vcc
	v_mov_b32_dpp v200, v80 quad_perm:[1,0,3,2] row_mask:0xf bank_mask:0xf
	v_cndmask_b32_dpp v201, v76, v200, vcc quad_perm:[1,0,3,2] row_mask:0xf bank_mask:0xf
	v_cndmask_b32_e32 v80, v201, v80, vcc
	v_cndmask_b32_e32 v76, v76, v201, vcc
	v_mov_b32_dpp v200, v81 quad_perm:[1,0,3,2] row_mask:0xf bank_mask:0xf
	v_cndmask_b32_dpp v201, v77, v200, vcc quad_perm:[1,0,3,2] row_mask:0xf bank_mask:0xf
	v_cndmask_b32_e32 v81, v201, v81, vcc
	v_cndmask_b32_e32 v77, v77, v201, vcc
	s_waitcnt vmcnt(24)
;     ...
; #pragma unroll
;     for (int ai = 0; ai < 2; ++ai)
; #pragma unroll
;       for (int m = 0; m < 4; ++m)
;         epi(brow + ai * HALF + wr * 64 + m * 16 + fr, bcol + wc * 32, fq, acc[ai][0][m][0], acc[ai][0][m][1], acc[ai][1][m][0], acc[ai][1][m][1]);
	v_pk_add_f32 v[236:237], v[70:71], v[236:237]
	v_pk_add_f32 v[238:239], v[72:73], v[238:239]
	v_pk_add_f32 v[240:241], v[66:67], v[240:241]
	v_pk_add_f32 v[242:243], v[68:69], v[242:243]
	v_pk_add_f32 v[244:245], v[78:79], v[244:245]
	v_pk_add_f32 v[246:247], v[80:81], v[246:247]
	v_pk_add_f32 v[248:249], v[74:75], v[248:249]
	v_pk_add_f32 v[250:251], v[76:77], v[250:251]
	global_store_dwordx4 v[150:151], v[236:239], off sc1
	global_store_dwordx4 v[152:153], v[240:243], off sc1
	global_store_dwordx4 v[150:151], v[244:247], off offset:512 sc1
	global_store_dwordx4 v[152:153], v[248:251], off offset:512 sc1
	s_nop 1
	s_mov_b64 s[6:7], 0xb0000
	v_lshl_add_u64 v[150:151], v[132:133], 0, s[6:7]
	v_lshl_add_u64 v[152:153], v[136:137], 0, s[6:7]
	global_load_dwordx4 v[236:239], v[150:151], off
	global_load_dwordx4 v[240:243], v[152:153], off
	global_load_dwordx4 v[244:247], v[150:151], off offset:512
	global_load_dwordx4 v[248:251], v[152:153], off offset:512
	v_mov_b32_dpp v200, v54 quad_perm:[1,0,3,2] row_mask:0xf bank_mask:0xf
	v_cndmask_b32_dpp v201, v50, v200, vcc quad_perm:[1,0,3,2] row_mask:0xf bank_mask:0xf
	v_cndmask_b32_e32 v54, v201, v54, vcc
	v_cndmask_b32_e32 v50, v50, v201, vcc
	v_mov_b32_dpp v200, v55 quad_perm:[1,0,3,2] row_mask:0xf bank_mask:0xf
	v_cndmask_b32_dpp v201, v51, v200, vcc quad_perm:[1,0,3,2] row_mask:0xf bank_mask:0xf
	v_cndmask_b32_e32 v55, v201, v55, vcc
	v_cndmask_b32_e32 v51, v51, v201, vcc
	v_mov_b32_dpp v200, v56 quad_perm:[1,0,3,2] row_mask:0xf bank_mask:0xf
	v_cndmask_b32_dpp v201, v52, v200, vcc quad_perm:[1,0,3,2] row_mask:0xf bank_mask:0xf
	v_cndmask_b32_e32 v56, v201, v56, vcc
	v_cndmask_b32_e32 v52, v52, v201, vcc
	v_mov_b32_dpp v200, v57 quad_perm:[1,0,3,2] row_mask:0xf bank_mask:0xf
	v_cndmask_b32_dpp v201, v53, v200, vcc quad_perm:[1,0,3,2] row_mask:0xf bank_mask:0xf
	v_cndmask_b32_e32 v57, v201, v57, vcc
	v_cndmask_b32_e32 v53, v53, v201, vcc
	v_mov_b32_dpp v200, v62 quad_perm:[1,0,3,2] row_mask:0xf bank_mask:0xf
	v_cndmask_b32_dpp v201, v58, v200, vcc quad_perm:[1,0,3,2] row_mask:0xf bank_mask:0xf
	v_cndmask_b32_e32 v62, v201, v62, vcc
	v_cndmask_b32_e32 v58, v58, v201, vcc
	v_mov_b32_dpp v200, v63 quad_perm:[1,0,3,2] row_mask:0xf bank_mask:0xf
	v_cndmask_b32_dpp v201, v59, v200, vcc quad_perm:[1,0,3,2] row_mask:0xf bank_mask:0xf
	v_cndmask_b32_e32 v63, v201, v63, vcc
	v_cndmask_b32_e32 v59, v59, v201, vcc
	v_mov_b32_dpp v200, v64 quad_perm:[1,0,3,2] row_mask:0xf bank_mask:0xf
	v_cndmask_b32_dpp v201, v60, v200, vcc quad_perm:[1,0,3,2] row_mask:0xf bank_mask:0xf
	v_cndmask_b32_e32 v64, v201, v64, vcc
	v_cndmask_b32_e32 v60, v60, v201, vcc
	v_mov_b32_dpp v200, v65 quad_perm:[1,0,3,2] row_mask:0xf bank_mask:0xf
	v_cndmask_b32_dpp v201, v61, v200, vcc quad_perm:[1,0,3,2] row_mask:0xf bank_mask:0xf
	v_cndmask_b32_e32 v65, v201, v65, vcc
	v_cndmask_b32_e32 v61, v61, v201, vcc
	s_waitcnt vmcnt(24)
	v_pk_add_f32 v[168:169], v[54:55], v[168:169]
	v_pk_add_f32 v[170:171], v[56:57], v[170:171]
	v_pk_add_f32 v[172:173], v[50:51], v[172:173]
	v_pk_add_f32 v[174:175], v[52:53], v[174:175]
	v_pk_add_f32 v[176:177], v[62:63], v[176:177]
	v_pk_add_f32 v[178:179], v[64:65], v[178:179]
	v_pk_add_f32 v[180:181], v[58:59], v[180:181]
	v_pk_add_f32 v[182:183], v[60:61], v[182:183]
	global_store_dwordx4 v[138:139], v[168:171], off sc1
	global_store_dwordx4 v[140:141], v[172:175], off sc1
	global_store_dwordx4 v[138:139], v[176:179], off offset:512 sc1
	global_store_dwordx4 v[140:141], v[180:183], off offset:512 sc1
	v_mov_b32_dpp v200, v38 quad_perm:[1,0,3,2] row_mask:0xf bank_mask:0xf
	v_cndmask_b32_dpp v201, v34, v200, vcc quad_perm:[1,0,3,2] row_mask:0xf bank_mask:0xf
	v_cndmask_b32_e32 v38, v201, v38, vcc
	v_cndmask_b32_e32 v34, v34, v201, vcc
	v_mov_b32_dpp v200, v39 quad_perm:[1,0,3,2] row_mask:0xf bank_mask:0xf
	v_cndmask_b32_dpp v201, v35, v200, vcc quad_perm:[1,0,3,2] row_mask:0xf bank_mask:0xf
	v_cndmask_b32_e32 v39, v201, v39, vcc
	v_cndmask_b32_e32 v35, v35, v201, vcc
	v_mov_b32_dpp v200, v40 quad_perm:[1,0,3,2] row_mask:0xf bank_mask:0xf
	v_cndmask_b32_dpp v201, v36, v200, vcc quad_perm:[1,0,3,2] row_mask:0xf bank_mask:0xf
	v_cndmask_b32_e32 v40, v201, v40, vcc
	v_cndmask_b32_e32 v36, v36, v201, vcc
	v_mov_b32_dpp v200, v41 quad_perm:[1,0,3,2] row_mask:0xf bank_mask:0xf
	v_cndmask_b32_dpp v201, v37, v200, vcc quad_perm:[1,0,3,2] row_mask:0xf bank_mask:0xf
	v_cndmask_b32_e32 v41, v201, v41, vcc
	v_cndmask_b32_e32 v37, v37, v201, vcc
	v_mov_b32_dpp v200, v46 quad_perm:[1,0,3,2] row_mask:0xf bank_mask:0xf
	v_cndmask_b32_dpp v201, v42, v200, vcc quad_perm:[1,0,3,2] row_mask:0xf bank_mask:0xf
	v_cndmask_b32_e32 v46, v201, v46, vcc
	v_cndmask_b32_e32 v42, v42, v201, vcc
	v_mov_b32_dpp v200, v47 quad_perm:[1,0,3,2] row_mask:0xf bank_mask:0xf
	v_cndmask_b32_dpp v201, v43, v200, vcc quad_perm:[1,0,3,2] row_mask:0xf bank_mask:0xf
	v_cndmask_b32_e32 v47, v201, v47, vcc
	v_cndmask_b32_e32 v43, v43, v201, vcc
	v_mov_b32_dpp v200, v48 quad_perm:[1,0,3,2] row_mask:0xf bank_mask:0xf
	v_cndmask_b32_dpp v201, v44, v200, vcc quad_perm:[1,0,3,2] row_mask:0xf bank_mask:0xf
	v_cndmask_b32_e32 v48, v201, v48, vcc
	v_cndmask_b32_e32 v44, v44, v201, vcc
	v_mov_b32_dpp v200, v49 quad_perm:[1,0,3,2] row_mask:0xf bank_mask:0xf
	v_cndmask_b32_dpp v201, v45, v200, vcc quad_perm:[1,0,3,2] row_mask:0xf bank_mask:0xf
	v_cndmask_b32_e32 v49, v201, v49, vcc
	v_cndmask_b32_e32 v45, v45, v201, vcc
	s_waitcnt vmcnt(20)
; #define WAIT_V(n) asm volatile("s_waitcnt vmcnt(" #n ")" ::: "memory")
;     ...
; #pragma unroll
;     for (int ai = 0; ai < 2; ++ai)
; #pragma unroll
;       for (int m = 0; m < 4; ++m)
;         epi(brow + ai * HALF + wr * 64 + m * 16 + fr, bcol + wc * 32, fq, acc[ai][0][m][0], acc[ai][0][m][1], acc[ai][1][m][0], acc[ai][1][m][1]);
;     ...
;   if (!have_next) { WAIT_V(0); __syncthreads(); }
	v_pk_add_f32 v[184:185], v[38:39], v[184:185]
	v_pk_add_f32 v[186:187], v[40:41], v[186:187]
	v_pk_add_f32 v[188:189], v[34:35], v[188:189]
	v_pk_add_f32 v[190:191], v[36:37], v[190:191]
	v_pk_add_f32 v[192:193], v[46:47], v[192:193]
	v_pk_add_f32 v[194:195], v[48:49], v[194:195]
	v_pk_add_f32 v[196:197], v[42:43], v[196:197]
	v_pk_add_f32 v[198:199], v[44:45], v[198:199]
	global_store_dwordx4 v[142:143], v[184:187], off sc1
	global_store_dwordx4 v[144:145], v[188:191], off sc1
	global_store_dwordx4 v[142:143], v[192:195], off offset:512 sc1
	global_store_dwordx4 v[144:145], v[196:199], off offset:512 sc1
	v_mov_b32_dpp v200, v22 quad_perm:[1,0,3,2] row_mask:0xf bank_mask:0xf
	v_cndmask_b32_dpp v201, v18, v200, vcc quad_perm:[1,0,3,2] row_mask:0xf bank_mask:0xf
	v_cndmask_b32_e32 v22, v201, v22, vcc
	v_cndmask_b32_e32 v18, v18, v201, vcc
	v_mov_b32_dpp v200, v23 quad_perm:[1,0,3,2] row_mask:0xf bank_mask:0xf
	v_cndmask_b32_dpp v201, v19, v200, vcc quad_perm:[1,0,3,2] row_mask:0xf bank_mask:0xf
	v_cndmask_b32_e32 v23, v201, v23, vcc
	v_cndmask_b32_e32 v19, v19, v201, vcc
	v_mov_b32_dpp v200, v24 quad_perm:[1,0,3,2] row_mask:0xf bank_mask:0xf
	v_cndmask_b32_dpp v201, v20, v200, vcc quad_perm:[1,0,3,2] row_mask:0xf bank_mask:0xf
	v_cndmask_b32_e32 v24, v201, v24, vcc
	v_cndmask_b32_e32 v20, v20, v201, vcc
	v_mov_b32_dpp v200, v25 quad_perm:[1,0,3,2] row_mask:0xf bank_mask:0xf
	v_cndmask_b32_dpp v201, v21, v200, vcc quad_perm:[1,0,3,2] row_mask:0xf bank_mask:0xf
	v_cndmask_b32_e32 v25, v201, v25, vcc
	v_cndmask_b32_e32 v21, v21, v201, vcc
	v_mov_b32_dpp v200, v30 quad_perm:[1,0,3,2] row_mask:0xf bank_mask:0xf
	v_cndmask_b32_dpp v201, v26, v200, vcc quad_perm:[1,0,3,2] row_mask:0xf bank_mask:0xf
	v_cndmask_b32_e32 v30, v201, v30, vcc
	v_cndmask_b32_e32 v26, v26, v201, vcc
	v_mov_b32_dpp v200, v31 quad_perm:[1,0,3,2] row_mask:0xf bank_mask:0xf
	v_cndmask_b32_dpp v201, v27, v200, vcc quad_perm:[1,0,3,2] row_mask:0xf bank_mask:0xf
	v_cndmask_b32_e32 v31, v201, v31, vcc
	v_cndmask_b32_e32 v27, v27, v201, vcc
	v_mov_b32_dpp v200, v32 quad_perm:[1,0,3,2] row_mask:0xf bank_mask:0xf
	v_cndmask_b32_dpp v201, v28, v200, vcc quad_perm:[1,0,3,2] row_mask:0xf bank_mask:0xf
	v_cndmask_b32_e32 v32, v201, v32, vcc
	v_cndmask_b32_e32 v28, v28, v201, vcc
	v_mov_b32_dpp v200, v33 quad_perm:[1,0,3,2] row_mask:0xf bank_mask:0xf
	v_cndmask_b32_dpp v201, v29, v200, vcc quad_perm:[1,0,3,2] row_mask:0xf bank_mask:0xf
	v_cndmask_b32_e32 v33, v201, v33, vcc
	v_cndmask_b32_e32 v29, v29, v201, vcc
	s_waitcnt vmcnt(16)
	v_pk_add_f32 v[220:221], v[22:23], v[220:221]
	v_pk_add_f32 v[222:223], v[24:25], v[222:223]
	v_pk_add_f32 v[224:225], v[18:19], v[224:225]
	v_pk_add_f32 v[226:227], v[20:21], v[226:227]
	v_pk_add_f32 v[228:229], v[30:31], v[228:229]
	v_pk_add_f32 v[230:231], v[32:33], v[230:231]
	v_pk_add_f32 v[232:233], v[26:27], v[232:233]
	v_pk_add_f32 v[234:235], v[28:29], v[234:235]
	global_store_dwordx4 v[146:147], v[220:223], off sc1
	global_store_dwordx4 v[148:149], v[224:227], off sc1
	global_store_dwordx4 v[146:147], v[228:231], off offset:512 sc1
	global_store_dwordx4 v[148:149], v[232:235], off offset:512 sc1
	v_mov_b32_dpp v200, v14 quad_perm:[1,0,3,2] row_mask:0xf bank_mask:0xf
	v_cndmask_b32_dpp v201, v6, v200, vcc quad_perm:[1,0,3,2] row_mask:0xf bank_mask:0xf
	v_cndmask_b32_e32 v14, v201, v14, vcc
	v_cndmask_b32_e32 v6, v6, v201, vcc
	v_mov_b32_dpp v200, v15 quad_perm:[1,0,3,2] row_mask:0xf bank_mask:0xf
	v_cndmask_b32_dpp v201, v7, v200, vcc quad_perm:[1,0,3,2] row_mask:0xf bank_mask:0xf
	v_cndmask_b32_e32 v15, v201, v15, vcc
	v_cndmask_b32_e32 v7, v7, v201, vcc
	v_mov_b32_dpp v200, v16 quad_perm:[1,0,3,2] row_mask:0xf bank_mask:0xf
	v_cndmask_b32_dpp v201, v8, v200, vcc quad_perm:[1,0,3,2] row_mask:0xf bank_mask:0xf
	v_cndmask_b32_e32 v16, v201, v16, vcc
	v_cndmask_b32_e32 v8, v8, v201, vcc
	v_mov_b32_dpp v200, v17 quad_perm:[1,0,3,2] row_mask:0xf bank_mask:0xf
	v_cndmask_b32_dpp v201, v9, v200, vcc quad_perm:[1,0,3,2] row_mask:0xf bank_mask:0xf
	v_cndmask_b32_e32 v17, v201, v17, vcc
	v_cndmask_b32_e32 v9, v9, v201, vcc
	v_mov_b32_dpp v200, v10 quad_perm:[1,0,3,2] row_mask:0xf bank_mask:0xf
	v_cndmask_b32_dpp v201, v2, v200, vcc quad_perm:[1,0,3,2] row_mask:0xf bank_mask:0xf
	v_cndmask_b32_e32 v10, v201, v10, vcc
	v_cndmask_b32_e32 v2, v2, v201, vcc
	v_mov_b32_dpp v200, v11 quad_perm:[1,0,3,2] row_mask:0xf bank_mask:0xf
	v_cndmask_b32_dpp v201, v3, v200, vcc quad_perm:[1,0,3,2] row_mask:0xf bank_mask:0xf
	v_cndmask_b32_e32 v11, v201, v11, vcc
	v_cndmask_b32_e32 v3, v3, v201, vcc
	v_mov_b32_dpp v200, v12 quad_perm:[1,0,3,2] row_mask:0xf bank_mask:0xf
	v_cndmask_b32_dpp v201, v4, v200, vcc quad_perm:[1,0,3,2] row_mask:0xf bank_mask:0xf
	v_cndmask_b32_e32 v12, v201, v12, vcc
	v_cndmask_b32_e32 v4, v4, v201, vcc
	v_mov_b32_dpp v200, v13 quad_perm:[1,0,3,2] row_mask:0xf bank_mask:0xf
	v_cndmask_b32_dpp v201, v5, v200, vcc quad_perm:[1,0,3,2] row_mask:0xf bank_mask:0xf
	v_cndmask_b32_e32 v13, v201, v13, vcc
	v_cndmask_b32_e32 v5, v5, v201, vcc
	s_waitcnt vmcnt(12)
	v_pk_add_f32 v[236:237], v[14:15], v[236:237]
	v_pk_add_f32 v[238:239], v[16:17], v[238:239]
	v_pk_add_f32 v[240:241], v[6:7], v[240:241]
	v_pk_add_f32 v[242:243], v[8:9], v[242:243]
	v_pk_add_f32 v[244:245], v[10:11], v[244:245]
	v_pk_add_f32 v[246:247], v[12:13], v[246:247]
	v_pk_add_f32 v[248:249], v[2:3], v[248:249]
	v_pk_add_f32 v[250:251], v[4:5], v[250:251]
	global_store_dwordx4 v[150:151], v[236:239], off sc1
	global_store_dwordx4 v[152:153], v[240:243], off sc1
	global_store_dwordx4 v[150:151], v[244:247], off offset:512 sc1
	global_store_dwordx4 v[152:153], v[248:251], off offset:512 sc1
	v_cmp_ne_u32_e64 s[6:7], 1, v0
	s_andn2_b64 vcc, exec, s[4:5]
	s_cbranch_vccnz .LBB0_1450
	s_waitcnt vmcnt(0)
	s_waitcnt lgkmcnt(0)
	s_barrier
	s_branch .LBB0_1450

.LBB0_1487:
	v_or_b32_e32 v0, s8, v140
	v_readlane_b32 s16, v253, 24
	v_add_u32_e32 v136, v0, v141
	v_readlane_b32 s17, v253, 25
	v_ashrrev_i32_e32 v137, 31, v136
	v_readlane_b32 s18, v253, 26
	v_readlane_b32 s19, v253, 27
	v_readlane_b32 s20, v253, 28
	v_readlane_b32 s21, v253, 29
	s_mov_b64 s[8:9], s[16:17]
	v_lshl_or_b32 v0, v139, 5, s90
	s_mov_b32 s6, 0x8000
	v_lshlrev_b64 v[138:139], 12, v[136:137]
	s_mov_b64 s[10:11], s[18:19]
	v_lshlrev_b32_e32 v20, 12, v140
	v_mov_b32_e32 v21, v1
	v_cmp_gt_i32_e32 vcc, s6, v136
	v_lshl_add_u64 v[18:19], s[8:9], 0, v[138:139]
	v_lshl_add_u64 v[134:135], s[10:11], 0, v[20:21]
	v_readlane_b32 s10, v253, 60
	v_cndmask_b32_e32 v19, v135, v19, vcc
	v_cndmask_b32_e32 v18, v134, v18, vcc
	v_readlane_b32 s11, v253, 61
	v_lshlrev_b64 v[132:133], 2, v[0:1]
	v_mov_b32_e32 v131, v1
	v_lshl_add_u64 v[20:21], s[10:11], 0, v[138:139]
	v_lshl_add_u64 v[18:19], v[18:19], 0, v[132:133]
	v_lshl_add_u64 v[20:21], v[20:21], 0, v[132:133]
	v_lshl_add_u64 v[148:149], v[18:19], 0, v[130:131]
	v_lshl_add_u64 v[152:153], v[20:21], 0, v[130:131]
	v_readlane_b32 s22, v253, 30
	v_readlane_b32 s23, v253, 31
	v_readlane_b32 s24, v253, 32
	v_readlane_b32 s25, v253, 33
	v_readlane_b32 s26, v253, 34
	v_readlane_b32 s27, v253, 35
	v_readlane_b32 s28, v253, 36
	v_readlane_b32 s29, v253, 37
	v_readlane_b32 s30, v253, 38
	v_readlane_b32 s31, v253, 39
	s_mov_b64 s[12:13], s[20:21]
	v_sub_co_u32_e32 v134, vcc, v152, v148
	v_subb_co_u32_e32 v135, vcc, v153, v149, vcc
	s_nop 0
	v_readfirstlane_b32 s98, v134
	v_readfirstlane_b32 s99, v135
	v_and_b32_e32 v134, 1, v210
	v_cmp_eq_u32_e32 vcc, 0, v134
	s_nop 1
	v_mov_b32_e32 v135, 0xfffff040
	v_cndmask_b32_e32 v134, v135, v1, vcc
	v_cndmask_b32_e32 v135, -1, v1, vcc
	v_lshl_add_u64 v[132:133], v[148:149], 0, v[134:135]
	s_mov_b64 s[96:97], 0x1000
	v_lshl_add_u64 v[136:137], v[132:133], 0, s[96:97]
	v_mov_b64_e32 v[138:139], v[132:133]
	v_mov_b64_e32 v[140:141], v[136:137]
	global_load_dwordx4 v[168:171], v[138:139], off
	global_load_dwordx4 v[172:175], v[140:141], off
	global_load_dwordx4 v[176:179], v[138:139], off offset:512
	global_load_dwordx4 v[180:183], v[140:141], off offset:512
	s_mov_b64 s[96:97], 0x10000
	v_lshl_add_u64 v[142:143], v[132:133], 0, s[96:97]
	v_lshl_add_u64 v[144:145], v[136:137], 0, s[96:97]
	global_load_dwordx4 v[184:187], v[142:143], off
	global_load_dwordx4 v[188:191], v[144:145], off
	global_load_dwordx4 v[192:195], v[142:143], off offset:512
	global_load_dwordx4 v[196:199], v[144:145], off offset:512
	s_mov_b64 s[96:97], 0x20000
	v_lshl_add_u64 v[146:147], v[132:133], 0, s[96:97]
	v_lshl_add_u64 v[148:149], v[136:137], 0, s[96:97]
	global_load_dwordx4 v[224:227], v[146:147], off
	global_load_dwordx4 v[228:231], v[148:149], off
	global_load_dwordx4 v[232:235], v[146:147], off offset:512
	global_load_dwordx4 v[236:239], v[148:149], off offset:512
	s_mov_b64 s[96:97], 0x30000
	v_lshl_add_u64 v[150:151], v[132:133], 0, s[96:97]
	v_lshl_add_u64 v[152:153], v[136:137], 0, s[96:97]
	global_load_dwordx4 v[240:243], v[150:151], off
	global_load_dwordx4 v[244:247], v[152:153], off
	global_load_dwordx4 v[248:251], v[150:151], off offset:512
	global_load_dwordx4 v[206:209], v[152:153], off offset:512
	v_mov_b32_dpp v200, v118 quad_perm:[1,0,3,2] row_mask:0xf bank_mask:0xf
	v_cndmask_b32_dpp v201, v114, v200, vcc quad_perm:[1,0,3,2] row_mask:0xf bank_mask:0xf
	v_cndmask_b32_e32 v118, v201, v118, vcc
	v_cndmask_b32_e32 v114, v114, v201, vcc
	v_mov_b32_dpp v200, v119 quad_perm:[1,0,3,2] row_mask:0xf bank_mask:0xf
	v_cndmask_b32_dpp v201, v115, v200, vcc quad_perm:[1,0,3,2] row_mask:0xf bank_mask:0xf
	v_cndmask_b32_e32 v119, v201, v119, vcc
	v_cndmask_b32_e32 v115, v115, v201, vcc
	v_mov_b32_dpp v200, v120 quad_perm:[1,0,3,2] row_mask:0xf bank_mask:0xf
	v_cndmask_b32_dpp v201, v116, v200, vcc quad_perm:[1,0,3,2] row_mask:0xf bank_mask:0xf
	v_cndmask_b32_e32 v120, v201, v120, vcc
	v_cndmask_b32_e32 v116, v116, v201, vcc
	v_mov_b32_dpp v200, v121 quad_perm:[1,0,3,2] row_mask:0xf bank_mask:0xf
	v_cndmask_b32_dpp v201, v117, v200, vcc quad_perm:[1,0,3,2] row_mask:0xf bank_mask:0xf
	v_cndmask_b32_e32 v121, v201, v121, vcc
	v_cndmask_b32_e32 v117, v117, v201, vcc
	v_mov_b32_dpp v200, v126 quad_perm:[1,0,3,2] row_mask:0xf bank_mask:0xf
	v_cndmask_b32_dpp v201, v122, v200, vcc quad_perm:[1,0,3,2] row_mask:0xf bank_mask:0xf
	v_cndmask_b32_e32 v126, v201, v126, vcc
	v_cndmask_b32_e32 v122, v122, v201, vcc
	v_mov_b32_dpp v200, v127 quad_perm:[1,0,3,2] row_mask:0xf bank_mask:0xf
	v_cndmask_b32_dpp v201, v123, v200, vcc quad_perm:[1,0,3,2] row_mask:0xf bank_mask:0xf
	v_cndmask_b32_e32 v127, v201, v127, vcc
	v_cndmask_b32_e32 v123, v123, v201, vcc
	v_mov_b32_dpp v200, v128 quad_perm:[1,0,3,2] row_mask:0xf bank_mask:0xf
	v_cndmask_b32_dpp v201, v124, v200, vcc quad_perm:[1,0,3,2] row_mask:0xf bank_mask:0xf
	v_cndmask_b32_e32 v128, v201, v128, vcc
	v_cndmask_b32_e32 v124, v124, v201, vcc
	v_mov_b32_dpp v200, v129 quad_perm:[1,0,3,2] row_mask:0xf bank_mask:0xf
	v_cndmask_b32_dpp v201, v125, v200, vcc quad_perm:[1,0,3,2] row_mask:0xf bank_mask:0xf
	v_cndmask_b32_e32 v129, v201, v129, vcc
	v_cndmask_b32_e32 v125, v125, v201, vcc
	s_waitcnt vmcnt(12)
	v_pk_add_f32 v[168:169], v[118:119], v[168:169]
	v_pk_add_f32 v[170:171], v[120:121], v[170:171]
	v_pk_add_f32 v[172:173], v[114:115], v[172:173]
	v_pk_add_f32 v[174:175], v[116:117], v[174:175]
	v_pk_add_f32 v[176:177], v[126:127], v[176:177]
	v_pk_add_f32 v[178:179], v[128:129], v[178:179]
	v_pk_add_f32 v[180:181], v[122:123], v[180:181]
	v_pk_add_f32 v[182:183], v[124:125], v[182:183]
	v_lshl_add_u64 v[202:203], v[138:139], 0, s[98:99]
	v_lshl_add_u64 v[204:205], v[140:141], 0, s[98:99]
	global_store_dwordx4 v[202:203], v[168:171], off sc1
	global_store_dwordx4 v[204:205], v[172:175], off sc1
	global_store_dwordx4 v[202:203], v[176:179], off offset:512 sc1
	global_store_dwordx4 v[204:205], v[180:183], off offset:512 sc1
	s_nop 1
	s_mov_b64 s[96:97], 0x80000
	v_lshl_add_u64 v[138:139], v[132:133], 0, s[96:97]
	v_lshl_add_u64 v[140:141], v[136:137], 0, s[96:97]
	global_load_dwordx4 v[168:171], v[138:139], off
	global_load_dwordx4 v[172:175], v[140:141], off
	global_load_dwordx4 v[176:179], v[138:139], off offset:512
	global_load_dwordx4 v[180:183], v[140:141], off offset:512
	v_mov_b32_dpp v200, v102 quad_perm:[1,0,3,2] row_mask:0xf bank_mask:0xf
	v_cndmask_b32_dpp v201, v98, v200, vcc quad_perm:[1,0,3,2] row_mask:0xf bank_mask:0xf
	v_cndmask_b32_e32 v102, v201, v102, vcc
	v_cndmask_b32_e32 v98, v98, v201, vcc
	v_mov_b32_dpp v200, v103 quad_perm:[1,0,3,2] row_mask:0xf bank_mask:0xf
	v_cndmask_b32_dpp v201, v99, v200, vcc quad_perm:[1,0,3,2] row_mask:0xf bank_mask:0xf
	v_cndmask_b32_e32 v103, v201, v103, vcc
	v_cndmask_b32_e32 v99, v99, v201, vcc
	v_mov_b32_dpp v200, v104 quad_perm:[1,0,3,2] row_mask:0xf bank_mask:0xf
	v_cndmask_b32_dpp v201, v100, v200, vcc quad_perm:[1,0,3,2] row_mask:0xf bank_mask:0xf
	v_cndmask_b32_e32 v104, v201, v104, vcc
	v_cndmask_b32_e32 v100, v100, v201, vcc
	v_mov_b32_dpp v200, v105 quad_perm:[1,0,3,2] row_mask:0xf bank_mask:0xf
	v_cndmask_b32_dpp v201, v101, v200, vcc quad_perm:[1,0,3,2] row_mask:0xf bank_mask:0xf
	v_cndmask_b32_e32 v105, v201, v105, vcc
	v_cndmask_b32_e32 v101, v101, v201, vcc
	v_mov_b32_dpp v200, v110 quad_perm:[1,0,3,2] row_mask:0xf bank_mask:0xf
	v_cndmask_b32_dpp v201, v106, v200, vcc quad_perm:[1,0,3,2] row_mask:0xf bank_mask:0xf
	v_cndmask_b32_e32 v110, v201, v110, vcc
	v_cndmask_b32_e32 v106, v106, v201, vcc
	v_mov_b32_dpp v200, v111 quad_perm:[1,0,3,2] row_mask:0xf bank_mask:0xf
	v_cndmask_b32_dpp v201, v107, v200, vcc quad_perm:[1,0,3,2] row_mask:0xf bank_mask:0xf
	v_cndmask_b32_e32 v111, v201, v111, vcc
	v_cndmask_b32_e32 v107, v107, v201, vcc
	v_mov_b32_dpp v200, v112 quad_perm:[1,0,3,2] row_mask:0xf bank_mask:0xf
	v_cndmask_b32_dpp v201, v108, v200, vcc quad_perm:[1,0,3,2] row_mask:0xf bank_mask:0xf
	v_cndmask_b32_e32 v112, v201, v112, vcc
	v_cndmask_b32_e32 v108, v108, v201, vcc
	v_mov_b32_dpp v200, v113 quad_perm:[1,0,3,2] row_mask:0xf bank_mask:0xf
	v_cndmask_b32_dpp v201, v109, v200, vcc quad_perm:[1,0,3,2] row_mask:0xf bank_mask:0xf
	v_cndmask_b32_e32 v113, v201, v113, vcc
	v_cndmask_b32_e32 v109, v109, v201, vcc
	s_waitcnt vmcnt(16)
	v_pk_add_f32 v[184:185], v[102:103], v[184:185]
	v_pk_add_f32 v[186:187], v[104:105], v[186:187]
	v_pk_add_f32 v[188:189], v[98:99], v[188:189]
	v_pk_add_f32 v[190:191], v[100:101], v[190:191]
	v_pk_add_f32 v[192:193], v[110:111], v[192:193]
	v_pk_add_f32 v[194:195], v[112:113], v[194:195]
	v_pk_add_f32 v[196:197], v[106:107], v[196:197]
	v_pk_add_f32 v[198:199], v[108:109], v[198:199]
	v_lshl_add_u64 v[202:203], v[142:143], 0, s[98:99]
	v_lshl_add_u64 v[204:205], v[144:145], 0, s[98:99]
	global_store_dwordx4 v[202:203], v[184:187], off sc1
	global_store_dwordx4 v[204:205], v[188:191], off sc1
	global_store_dwordx4 v[202:203], v[192:195], off offset:512 sc1
	global_store_dwordx4 v[204:205], v[196:199], off offset:512 sc1
	s_nop 1
	s_mov_b64 s[96:97], 0x90000
	v_lshl_add_u64 v[142:143], v[132:133], 0, s[96:97]
	v_lshl_add_u64 v[144:145], v[136:137], 0, s[96:97]
	global_load_dwordx4 v[184:187], v[142:143], off
	global_load_dwordx4 v[188:191], v[144:145], off
	global_load_dwordx4 v[192:195], v[142:143], off offset:512
	global_load_dwordx4 v[196:199], v[144:145], off offset:512
	v_mov_b32_dpp v200, v86 quad_perm:[1,0,3,2] row_mask:0xf bank_mask:0xf
	v_cndmask_b32_dpp v201, v82, v200, vcc quad_perm:[1,0,3,2] row_mask:0xf bank_mask:0xf
	v_cndmask_b32_e32 v86, v201, v86, vcc
	v_cndmask_b32_e32 v82, v82, v201, vcc
	v_mov_b32_dpp v200, v87 quad_perm:[1,0,3,2] row_mask:0xf bank_mask:0xf
	v_cndmask_b32_dpp v201, v83, v200, vcc quad_perm:[1,0,3,2] row_mask:0xf bank_mask:0xf
	v_cndmask_b32_e32 v87, v201, v87, vcc
	v_cndmask_b32_e32 v83, v83, v201, vcc
	v_mov_b32_dpp v200, v88 quad_perm:[1,0,3,2] row_mask:0xf bank_mask:0xf
	v_cndmask_b32_dpp v201, v84, v200, vcc quad_perm:[1,0,3,2] row_mask:0xf bank_mask:0xf
	v_cndmask_b32_e32 v88, v201, v88, vcc
	v_cndmask_b32_e32 v84, v84, v201, vcc
	v_mov_b32_dpp v200, v89 quad_perm:[1,0,3,2] row_mask:0xf bank_mask:0xf
	v_cndmask_b32_dpp v201, v85, v200, vcc quad_perm:[1,0,3,2] row_mask:0xf bank_mask:0xf
	v_cndmask_b32_e32 v89, v201, v89, vcc
	v_cndmask_b32_e32 v85, v85, v201, vcc
	v_mov_b32_dpp v200, v94 quad_perm:[1,0,3,2] row_mask:0xf bank_mask:0xf
	v_cndmask_b32_dpp v201, v90, v200, vcc quad_perm:[1,0,3,2] row_mask:0xf bank_mask:0xf
	v_cndmask_b32_e32 v94, v201, v94, vcc
	v_cndmask_b32_e32 v90, v90, v201, vcc
	v_mov_b32_dpp v200, v95 quad_perm:[1,0,3,2] row_mask:0xf bank_mask:0xf
	v_cndmask_b32_dpp v201, v91, v200, vcc quad_perm:[1,0,3,2] row_mask:0xf bank_mask:0xf
	v_cndmask_b32_e32 v95, v201, v95, vcc
	v_cndmask_b32_e32 v91, v91, v201, vcc
	v_mov_b32_dpp v200, v96 quad_perm:[1,0,3,2] row_mask:0xf bank_mask:0xf
	v_cndmask_b32_dpp v201, v92, v200, vcc quad_perm:[1,0,3,2] row_mask:0xf bank_mask:0xf
	v_cndmask_b32_e32 v96, v201, v96, vcc
	v_cndmask_b32_e32 v92, v92, v201, vcc
	v_mov_b32_dpp v200, v97 quad_perm:[1,0,3,2] row_mask:0xf bank_mask:0xf
	v_cndmask_b32_dpp v201, v93, v200, vcc quad_perm:[1,0,3,2] row_mask:0xf bank_mask:0xf
	v_cndmask_b32_e32 v97, v201, v97, vcc
	v_cndmask_b32_e32 v93, v93, v201, vcc
	s_waitcnt vmcnt(20)
	v_pk_add_f32 v[224:225], v[86:87], v[224:225]
	v_pk_add_f32 v[226:227], v[88:89], v[226:227]
	v_pk_add_f32 v[228:229], v[82:83], v[228:229]
	v_pk_add_f32 v[230:231], v[84:85], v[230:231]
	v_pk_add_f32 v[232:233], v[94:95], v[232:233]
	v_pk_add_f32 v[234:235], v[96:97], v[234:235]
	v_pk_add_f32 v[236:237], v[90:91], v[236:237]
	v_pk_add_f32 v[238:239], v[92:93], v[238:239]
	v_lshl_add_u64 v[202:203], v[146:147], 0, s[98:99]
	v_lshl_add_u64 v[204:205], v[148:149], 0, s[98:99]
	global_store_dwordx4 v[202:203], v[224:227], off sc1
	global_store_dwordx4 v[204:205], v[228:231], off sc1
	global_store_dwordx4 v[202:203], v[232:235], off offset:512 sc1
	global_store_dwordx4 v[204:205], v[236:239], off offset:512 sc1
	s_nop 1
	s_mov_b64 s[96:97], 0xa0000
	v_lshl_add_u64 v[146:147], v[132:133], 0, s[96:97]
	v_lshl_add_u64 v[148:149], v[136:137], 0, s[96:97]
	global_load_dwordx4 v[224:227], v[146:147], off
	global_load_dwordx4 v[228:231], v[148:149], off
	global_load_dwordx4 v[232:235], v[146:147], off offset:512
	global_load_dwordx4 v[236:239], v[148:149], off offset:512
	v_mov_b32_dpp v200, v70 quad_perm:[1,0,3,2] row_mask:0xf bank_mask:0xf
	v_cndmask_b32_dpp v201, v66, v200, vcc quad_perm:[1,0,3,2] row_mask:0xf bank_mask:0xf
	v_cndmask_b32_e32 v70, v201, v70, vcc
	v_cndmask_b32_e32 v66, v66, v201, vcc
	v_mov_b32_dpp v200, v71 quad_perm:[1,0,3,2] row_mask:0xf bank_mask:0xf
	v_cndmask_b32_dpp v201, v67, v200, vcc quad_perm:[1,0,3,2] row_mask:0xf bank_mask:0xf
	v_cndmask_b32_e32 v71, v201, v71, vcc
	v_cndmask_b32_e32 v67, v67, v201, vcc
	v_mov_b32_dpp v200, v72 quad_perm:[1,0,3,2] row_mask:0xf bank_mask:0xf
	v_cndmask_b32_dpp v201, v68, v200, vcc quad_perm:[1,0,3,2] row_mask:0xf bank_mask:0xf
	v_cndmask_b32_e32 v72, v201, v72, vcc
	v_cndmask_b32_e32 v68, v68, v201, vcc
	v_mov_b32_dpp v200, v73 quad_perm:[1,0,3,2] row_mask:0xf bank_mask:0xf
	v_cndmask_b32_dpp v201, v69, v200, vcc quad_perm:[1,0,3,2] row_mask:0xf bank_mask:0xf
	v_cndmask_b32_e32 v73, v201, v73, vcc
	v_cndmask_b32_e32 v69, v69, v201, vcc
	v_mov_b32_dpp v200, v78 quad_perm:[1,0,3,2] row_mask:0xf bank_mask:0xf
	v_cndmask_b32_dpp v201, v74, v200, vcc quad_perm:[1,0,3,2] row_mask:0xf bank_mask:0xf
	v_cndmask_b32_e32 v78, v201, v78, vcc
	v_cndmask_b32_e32 v74, v74, v201, vcc
	v_mov_b32_dpp v200, v79 quad_perm:[1,0,3,2] row_mask:0xf bank_mask:0xf
	v_cndmask_b32_dpp v201, v75, v200, vcc quad_perm:[1,0,3,2] row_mask:0xf bank_mask:0xf
	v_cndmask_b32_e32 v79, v201, v79, vcc
	v_cndmask_b32_e32 v75, v75, v201, vcc
	v_mov_b32_dpp v200, v80 quad_perm:[1,0,3,2] row_mask:0xf bank_mask:0xf
	v_cndmask_b32_dpp v201, v76, v200, vcc quad_perm:[1,0,3,2] row_mask:0xf bank_mask:0xf
	v_cndmask_b32_e32 v80, v201, v80, vcc
	v_cndmask_b32_e32 v76, v76, v201, vcc
	v_mov_b32_dpp v200, v81 quad_perm:[1,0,3,2] row_mask:0xf bank_mask:0xf
	v_cndmask_b32_dpp v201, v77, v200, vcc quad_perm:[1,0,3,2] row_mask:0xf bank_mask:0xf
	v_cndmask_b32_e32 v81, v201, v81, vcc
	v_cndmask_b32_e32 v77, v77, v201, vcc
	s_waitcnt vmcnt(24)
	v_pk_add_f32 v[240:241], v[70:71], v[240:241]
	v_pk_add_f32 v[242:243], v[72:73], v[242:243]
	v_pk_add_f32 v[244:245], v[66:67], v[244:245]
	v_pk_add_f32 v[246:247], v[68:69], v[246:247]
	v_pk_add_f32 v[248:249], v[78:79], v[248:249]
	v_pk_add_f32 v[250:251], v[80:81], v[250:251]
	v_pk_add_f32 v[206:207], v[74:75], v[206:207]
	v_pk_add_f32 v[208:209], v[76:77], v[208:209]
	v_lshl_add_u64 v[202:203], v[150:151], 0, s[98:99]
	v_lshl_add_u64 v[204:205], v[152:153], 0, s[98:99]
	global_store_dwordx4 v[202:203], v[240:243], off sc1
	global_store_dwordx4 v[204:205], v[244:247], off sc1
	global_store_dwordx4 v[202:203], v[248:251], off offset:512 sc1
	global_store_dwordx4 v[204:205], v[206:209], off offset:512 sc1
	s_nop 1
	s_mov_b64 s[96:97], 0xb0000
	v_lshl_add_u64 v[150:151], v[132:133], 0, s[96:97]
	v_lshl_add_u64 v[152:153], v[136:137], 0, s[96:97]
	global_load_dwordx4 v[240:243], v[150:151], off
	global_load_dwordx4 v[244:247], v[152:153], off
	global_load_dwordx4 v[248:251], v[150:151], off offset:512
	global_load_dwordx4 v[206:209], v[152:153], off offset:512
	v_mov_b32_dpp v200, v54 quad_perm:[1,0,3,2] row_mask:0xf bank_mask:0xf
	v_cndmask_b32_dpp v201, v50, v200, vcc quad_perm:[1,0,3,2] row_mask:0xf bank_mask:0xf
	v_cndmask_b32_e32 v54, v201, v54, vcc
	v_cndmask_b32_e32 v50, v50, v201, vcc
	v_mov_b32_dpp v200, v55 quad_perm:[1,0,3,2] row_mask:0xf bank_mask:0xf
	v_cndmask_b32_dpp v201, v51, v200, vcc quad_perm:[1,0,3,2] row_mask:0xf bank_mask:0xf
	v_cndmask_b32_e32 v55, v201, v55, vcc
	v_cndmask_b32_e32 v51, v51, v201, vcc
	v_mov_b32_dpp v200, v56 quad_perm:[1,0,3,2] row_mask:0xf bank_mask:0xf
	v_cndmask_b32_dpp v201, v52, v200, vcc quad_perm:[1,0,3,2] row_mask:0xf bank_mask:0xf
	v_cndmask_b32_e32 v56, v201, v56, vcc
	v_cndmask_b32_e32 v52, v52, v201, vcc
	v_mov_b32_dpp v200, v57 quad_perm:[1,0,3,2] row_mask:0xf bank_mask:0xf
	v_cndmask_b32_dpp v201, v53, v200, vcc quad_perm:[1,0,3,2] row_mask:0xf bank_mask:0xf
	v_cndmask_b32_e32 v57, v201, v57, vcc
	v_cndmask_b32_e32 v53, v53, v201, vcc
	v_mov_b32_dpp v200, v62 quad_perm:[1,0,3,2] row_mask:0xf bank_mask:0xf
	v_cndmask_b32_dpp v201, v58, v200, vcc quad_perm:[1,0,3,2] row_mask:0xf bank_mask:0xf
	v_cndmask_b32_e32 v62, v201, v62, vcc
	v_cndmask_b32_e32 v58, v58, v201, vcc
	v_mov_b32_dpp v200, v63 quad_perm:[1,0,3,2] row_mask:0xf bank_mask:0xf
	v_cndmask_b32_dpp v201, v59, v200, vcc quad_perm:[1,0,3,2] row_mask:0xf bank_mask:0xf
	v_cndmask_b32_e32 v63, v201, v63, vcc
	v_cndmask_b32_e32 v59, v59, v201, vcc
	v_mov_b32_dpp v200, v64 quad_perm:[1,0,3,2] row_mask:0xf bank_mask:0xf
	v_cndmask_b32_dpp v201, v60, v200, vcc quad_perm:[1,0,3,2] row_mask:0xf bank_mask:0xf
	v_cndmask_b32_e32 v64, v201, v64, vcc
	v_cndmask_b32_e32 v60, v60, v201, vcc
	v_mov_b32_dpp v200, v65 quad_perm:[1,0,3,2] row_mask:0xf bank_mask:0xf
	v_cndmask_b32_dpp v201, v61, v200, vcc quad_perm:[1,0,3,2] row_mask:0xf bank_mask:0xf
	v_cndmask_b32_e32 v65, v201, v65, vcc
	v_cndmask_b32_e32 v61, v61, v201, vcc
	s_waitcnt vmcnt(24)
	v_pk_add_f32 v[168:169], v[54:55], v[168:169]
	v_pk_add_f32 v[170:171], v[56:57], v[170:171]
	v_pk_add_f32 v[172:173], v[50:51], v[172:173]
	v_pk_add_f32 v[174:175], v[52:53], v[174:175]
	v_pk_add_f32 v[176:177], v[62:63], v[176:177]
	v_pk_add_f32 v[178:179], v[64:65], v[178:179]
	v_pk_add_f32 v[180:181], v[58:59], v[180:181]
	v_pk_add_f32 v[182:183], v[60:61], v[182:183]
	v_lshl_add_u64 v[202:203], v[138:139], 0, s[98:99]
	v_lshl_add_u64 v[204:205], v[140:141], 0, s[98:99]
	global_store_dwordx4 v[202:203], v[168:171], off sc1
	global_store_dwordx4 v[204:205], v[172:175], off sc1
	global_store_dwordx4 v[202:203], v[176:179], off offset:512 sc1
	global_store_dwordx4 v[204:205], v[180:183], off offset:512 sc1
	v_mov_b32_dpp v200, v38 quad_perm:[1,0,3,2] row_mask:0xf bank_mask:0xf
	v_cndmask_b32_dpp v201, v34, v200, vcc quad_perm:[1,0,3,2] row_mask:0xf bank_mask:0xf
	v_cndmask_b32_e32 v38, v201, v38, vcc
	v_cndmask_b32_e32 v34, v34, v201, vcc
	v_mov_b32_dpp v200, v39 quad_perm:[1,0,3,2] row_mask:0xf bank_mask:0xf
	v_cndmask_b32_dpp v201, v35, v200, vcc quad_perm:[1,0,3,2] row_mask:0xf bank_mask:0xf
	v_cndmask_b32_e32 v39, v201, v39, vcc
	v_cndmask_b32_e32 v35, v35, v201, vcc
	v_mov_b32_dpp v200, v40 quad_perm:[1,0,3,2] row_mask:0xf bank_mask:0xf
	v_cndmask_b32_dpp v201, v36, v200, vcc quad_perm:[1,0,3,2] row_mask:0xf bank_mask:0xf
	v_cndmask_b32_e32 v40, v201, v40, vcc
	v_cndmask_b32_e32 v36, v36, v201, vcc
	v_mov_b32_dpp v200, v41 quad_perm:[1,0,3,2] row_mask:0xf bank_mask:0xf
	v_cndmask_b32_dpp v201, v37, v200, vcc quad_perm:[1,0,3,2] row_mask:0xf bank_mask:0xf
	v_cndmask_b32_e32 v41, v201, v41, vcc
	v_cndmask_b32_e32 v37, v37, v201, vcc
	v_mov_b32_dpp v200, v46 quad_perm:[1,0,3,2] row_mask:0xf bank_mask:0xf
	v_cndmask_b32_dpp v201, v42, v200, vcc quad_perm:[1,0,3,2] row_mask:0xf bank_mask:0xf
	v_cndmask_b32_e32 v46, v201, v46, vcc
	v_cndmask_b32_e32 v42, v42, v201, vcc
	v_mov_b32_dpp v200, v47 quad_perm:[1,0,3,2] row_mask:0xf bank_mask:0xf
	v_cndmask_b32_dpp v201, v43, v200, vcc quad_perm:[1,0,3,2] row_mask:0xf bank_mask:0xf
	v_cndmask_b32_e32 v47, v201, v47, vcc
	v_cndmask_b32_e32 v43, v43, v201, vcc
	v_mov_b32_dpp v200, v48 quad_perm:[1,0,3,2] row_mask:0xf bank_mask:0xf
	v_cndmask_b32_dpp v201, v44, v200, vcc quad_perm:[1,0,3,2] row_mask:0xf bank_mask:0xf
	v_cndmask_b32_e32 v48, v201, v48, vcc
	v_cndmask_b32_e32 v44, v44, v201, vcc
	v_mov_b32_dpp v200, v49 quad_perm:[1,0,3,2] row_mask:0xf bank_mask:0xf
	v_cndmask_b32_dpp v201, v45, v200, vcc quad_perm:[1,0,3,2] row_mask:0xf bank_mask:0xf
	v_cndmask_b32_e32 v49, v201, v49, vcc
	v_cndmask_b32_e32 v45, v45, v201, vcc
	s_waitcnt vmcnt(20)
	v_pk_add_f32 v[184:185], v[38:39], v[184:185]
	v_pk_add_f32 v[186:187], v[40:41], v[186:187]
	v_pk_add_f32 v[188:189], v[34:35], v[188:189]
	v_pk_add_f32 v[190:191], v[36:37], v[190:191]
	v_pk_add_f32 v[192:193], v[46:47], v[192:193]
	v_pk_add_f32 v[194:195], v[48:49], v[194:195]
	v_pk_add_f32 v[196:197], v[42:43], v[196:197]
	v_pk_add_f32 v[198:199], v[44:45], v[198:199]
	v_lshl_add_u64 v[202:203], v[142:143], 0, s[98:99]
	v_lshl_add_u64 v[204:205], v[144:145], 0, s[98:99]
	global_store_dwordx4 v[202:203], v[184:187], off sc1
	global_store_dwordx4 v[204:205], v[188:191], off sc1
	global_store_dwordx4 v[202:203], v[192:195], off offset:512 sc1
	global_store_dwordx4 v[204:205], v[196:199], off offset:512 sc1
	v_mov_b32_dpp v200, v22 quad_perm:[1,0,3,2] row_mask:0xf bank_mask:0xf
	v_cndmask_b32_dpp v201, v220, v200, vcc quad_perm:[1,0,3,2] row_mask:0xf bank_mask:0xf
	v_cndmask_b32_e32 v22, v201, v22, vcc
	v_cndmask_b32_e32 v220, v220, v201, vcc
	v_mov_b32_dpp v200, v23 quad_perm:[1,0,3,2] row_mask:0xf bank_mask:0xf
	v_cndmask_b32_dpp v201, v221, v200, vcc quad_perm:[1,0,3,2] row_mask:0xf bank_mask:0xf
	v_cndmask_b32_e32 v23, v201, v23, vcc
	v_cndmask_b32_e32 v221, v221, v201, vcc
	v_mov_b32_dpp v200, v24 quad_perm:[1,0,3,2] row_mask:0xf bank_mask:0xf
	v_cndmask_b32_dpp v201, v222, v200, vcc quad_perm:[1,0,3,2] row_mask:0xf bank_mask:0xf
	v_cndmask_b32_e32 v24, v201, v24, vcc
	v_cndmask_b32_e32 v222, v222, v201, vcc
	v_mov_b32_dpp v200, v25 quad_perm:[1,0,3,2] row_mask:0xf bank_mask:0xf
	v_cndmask_b32_dpp v201, v223, v200, vcc quad_perm:[1,0,3,2] row_mask:0xf bank_mask:0xf
	v_cndmask_b32_e32 v25, v201, v25, vcc
	v_cndmask_b32_e32 v223, v223, v201, vcc
	v_mov_b32_dpp v200, v30 quad_perm:[1,0,3,2] row_mask:0xf bank_mask:0xf
	v_cndmask_b32_dpp v201, v26, v200, vcc quad_perm:[1,0,3,2] row_mask:0xf bank_mask:0xf
	v_cndmask_b32_e32 v30, v201, v30, vcc
	v_cndmask_b32_e32 v26, v26, v201, vcc
	v_mov_b32_dpp v200, v31 quad_perm:[1,0,3,2] row_mask:0xf bank_mask:0xf
	v_cndmask_b32_dpp v201, v27, v200, vcc quad_perm:[1,0,3,2] row_mask:0xf bank_mask:0xf
	v_cndmask_b32_e32 v31, v201, v31, vcc
	v_cndmask_b32_e32 v27, v27, v201, vcc
	v_mov_b32_dpp v200, v32 quad_perm:[1,0,3,2] row_mask:0xf bank_mask:0xf
	v_cndmask_b32_dpp v201, v28, v200, vcc quad_perm:[1,0,3,2] row_mask:0xf bank_mask:0xf
	v_cndmask_b32_e32 v32, v201, v32, vcc
	v_cndmask_b32_e32 v28, v28, v201, vcc
	v_mov_b32_dpp v200, v33 quad_perm:[1,0,3,2] row_mask:0xf bank_mask:0xf
	v_cndmask_b32_dpp v201, v29, v200, vcc quad_perm:[1,0,3,2] row_mask:0xf bank_mask:0xf
	v_cndmask_b32_e32 v33, v201, v33, vcc
	v_cndmask_b32_e32 v29, v29, v201, vcc
	s_waitcnt vmcnt(16)
; #define WAIT_V(n) asm volatile("s_waitcnt vmcnt(" #n ")" ::: "memory")
;     ...
;   if (!have_next) { WAIT_V(0); __syncthreads(); }
	v_pk_add_f32 v[224:225], v[22:23], v[224:225]
	v_pk_add_f32 v[226:227], v[24:25], v[226:227]
	v_pk_add_f32 v[228:229], v[220:221], v[228:229]
	v_pk_add_f32 v[230:231], v[222:223], v[230:231]
	v_pk_add_f32 v[232:233], v[30:31], v[232:233]
	v_pk_add_f32 v[234:235], v[32:33], v[234:235]
	v_pk_add_f32 v[236:237], v[26:27], v[236:237]
	v_pk_add_f32 v[238:239], v[28:29], v[238:239]
	v_lshl_add_u64 v[202:203], v[146:147], 0, s[98:99]
	v_lshl_add_u64 v[204:205], v[148:149], 0, s[98:99]
	global_store_dwordx4 v[202:203], v[224:227], off sc1
	global_store_dwordx4 v[204:205], v[228:231], off sc1
	global_store_dwordx4 v[202:203], v[232:235], off offset:512 sc1
	global_store_dwordx4 v[204:205], v[236:239], off offset:512 sc1
	v_mov_b32_dpp v200, v6 quad_perm:[1,0,3,2] row_mask:0xf bank_mask:0xf
	v_cndmask_b32_dpp v201, v2, v200, vcc quad_perm:[1,0,3,2] row_mask:0xf bank_mask:0xf
	v_cndmask_b32_e32 v6, v201, v6, vcc
	v_cndmask_b32_e32 v2, v2, v201, vcc
	v_mov_b32_dpp v200, v7 quad_perm:[1,0,3,2] row_mask:0xf bank_mask:0xf
	v_cndmask_b32_dpp v201, v3, v200, vcc quad_perm:[1,0,3,2] row_mask:0xf bank_mask:0xf
	v_cndmask_b32_e32 v7, v201, v7, vcc
	v_cndmask_b32_e32 v3, v3, v201, vcc
	v_mov_b32_dpp v200, v8 quad_perm:[1,0,3,2] row_mask:0xf bank_mask:0xf
	v_cndmask_b32_dpp v201, v4, v200, vcc quad_perm:[1,0,3,2] row_mask:0xf bank_mask:0xf
	v_cndmask_b32_e32 v8, v201, v8, vcc
	v_cndmask_b32_e32 v4, v4, v201, vcc
	v_mov_b32_dpp v200, v9 quad_perm:[1,0,3,2] row_mask:0xf bank_mask:0xf
	v_cndmask_b32_dpp v201, v5, v200, vcc quad_perm:[1,0,3,2] row_mask:0xf bank_mask:0xf
	v_cndmask_b32_e32 v9, v201, v9, vcc
	v_cndmask_b32_e32 v5, v5, v201, vcc
	v_mov_b32_dpp v200, v14 quad_perm:[1,0,3,2] row_mask:0xf bank_mask:0xf
	v_cndmask_b32_dpp v201, v10, v200, vcc quad_perm:[1,0,3,2] row_mask:0xf bank_mask:0xf
	v_cndmask_b32_e32 v14, v201, v14, vcc
	v_cndmask_b32_e32 v10, v10, v201, vcc
	v_mov_b32_dpp v200, v15 quad_perm:[1,0,3,2] row_mask:0xf bank_mask:0xf
	v_cndmask_b32_dpp v201, v11, v200, vcc quad_perm:[1,0,3,2] row_mask:0xf bank_mask:0xf
	v_cndmask_b32_e32 v15, v201, v15, vcc
	v_cndmask_b32_e32 v11, v11, v201, vcc
	v_mov_b32_dpp v200, v16 quad_perm:[1,0,3,2] row_mask:0xf bank_mask:0xf
	v_cndmask_b32_dpp v201, v12, v200, vcc quad_perm:[1,0,3,2] row_mask:0xf bank_mask:0xf
	v_cndmask_b32_e32 v16, v201, v16, vcc
	v_cndmask_b32_e32 v12, v12, v201, vcc
	v_mov_b32_dpp v200, v17 quad_perm:[1,0,3,2] row_mask:0xf bank_mask:0xf
	v_cndmask_b32_dpp v201, v13, v200, vcc quad_perm:[1,0,3,2] row_mask:0xf bank_mask:0xf
	v_cndmask_b32_e32 v17, v201, v17, vcc
	v_cndmask_b32_e32 v13, v13, v201, vcc
	s_waitcnt vmcnt(12)
	v_pk_add_f32 v[240:241], v[6:7], v[240:241]
	v_pk_add_f32 v[242:243], v[8:9], v[242:243]
	v_pk_add_f32 v[244:245], v[2:3], v[244:245]
	v_pk_add_f32 v[246:247], v[4:5], v[246:247]
	v_pk_add_f32 v[248:249], v[14:15], v[248:249]
	v_pk_add_f32 v[250:251], v[16:17], v[250:251]
	v_pk_add_f32 v[206:207], v[10:11], v[206:207]
	v_pk_add_f32 v[208:209], v[12:13], v[208:209]
	v_lshl_add_u64 v[202:203], v[150:151], 0, s[98:99]
	v_lshl_add_u64 v[204:205], v[152:153], 0, s[98:99]
	global_store_dwordx4 v[202:203], v[240:243], off sc1
	global_store_dwordx4 v[204:205], v[244:247], off sc1
	global_store_dwordx4 v[202:203], v[248:251], off offset:512 sc1
	global_store_dwordx4 v[204:205], v[206:209], off offset:512 sc1
	s_andn2_b64 vcc, exec, s[4:5]
	s_cbranch_vccnz .LBB0_1474
	s_waitcnt vmcnt(0)
	s_waitcnt lgkmcnt(0)
	s_barrier
	s_branch .LBB0_1474

;     ...
; #pragma unroll
;     for (int ai = 0; ai < 2; ++ai)
; #pragma unroll
;       for (int m = 0; m < 4; ++m)
;         epi(brow + ai * HALF + wr * 64 + m * 16 + fr, bcol + wc * 32, fq, acc[ai][0][m][0], acc[ai][0][m][1], acc[ai][1][m][0], acc[ai][1][m][1]);
.LBB0_1564:
	v_or_b32_e32 v0, s16, v140
	v_add_u32_e32 v136, v0, v141
	v_ashrrev_i32_e32 v137, 31, v136
	v_readlane_b32 s4, v253, 60
	v_lshl_or_b32 v0, v139, 5, s15
	v_lshlrev_b64 v[132:133], 12, v[136:137]
	v_readlane_b32 s5, v253, 61
	v_lshlrev_b64 v[134:135], 2, v[0:1]
	v_mov_b32_e32 v131, v1
	v_lshl_add_u64 v[132:133], s[4:5], 0, v[132:133]
	v_lshl_add_u64 v[132:133], v[132:133], 0, v[134:135]
	v_lshl_add_u64 v[132:133], v[132:133], 0, v[130:131]
	v_cndmask_b32_e64 v0, 0, 1, s[2:3]
	v_and_b32_e32 v134, 1, v210
	v_cmp_eq_u32_e32 vcc, 0, v134
	s_nop 1
	v_mov_b32_e32 v135, 0xfffff040
	v_cndmask_b32_e32 v134, v135, v1, vcc
	v_cndmask_b32_e32 v135, -1, v1, vcc
	v_lshl_add_u64 v[132:133], v[132:133], 0, v[134:135]
	s_mov_b64 s[4:5], 0x1000
	v_lshl_add_u64 v[136:137], v[132:133], 0, s[4:5]
	v_mov_b64_e32 v[138:139], v[132:133]
	v_mov_b64_e32 v[140:141], v[136:137]
	global_load_dwordx4 v[168:171], v[138:139], off
	global_load_dwordx4 v[172:175], v[140:141], off
	global_load_dwordx4 v[176:179], v[138:139], off offset:512
	global_load_dwordx4 v[180:183], v[140:141], off offset:512
	s_mov_b64 s[4:5], 0x10000
	v_lshl_add_u64 v[142:143], v[132:133], 0, s[4:5]
	v_lshl_add_u64 v[144:145], v[136:137], 0, s[4:5]
	global_load_dwordx4 v[184:187], v[142:143], off
	global_load_dwordx4 v[188:191], v[144:145], off
	global_load_dwordx4 v[192:195], v[142:143], off offset:512
	global_load_dwordx4 v[196:199], v[144:145], off offset:512
	s_mov_b64 s[4:5], 0x20000
	v_lshl_add_u64 v[146:147], v[132:133], 0, s[4:5]
	v_lshl_add_u64 v[148:149], v[136:137], 0, s[4:5]
	global_load_dwordx4 v[220:223], v[146:147], off
	global_load_dwordx4 v[224:227], v[148:149], off
	global_load_dwordx4 v[228:231], v[146:147], off offset:512
	global_load_dwordx4 v[232:235], v[148:149], off offset:512
	s_mov_b64 s[4:5], 0x30000
	v_lshl_add_u64 v[150:151], v[132:133], 0, s[4:5]
	v_lshl_add_u64 v[152:153], v[136:137], 0, s[4:5]
	global_load_dwordx4 v[236:239], v[150:151], off
	global_load_dwordx4 v[240:243], v[152:153], off
	global_load_dwordx4 v[244:247], v[150:151], off offset:512
	global_load_dwordx4 v[248:251], v[152:153], off offset:512
	v_mov_b32_dpp v200, v118 quad_perm:[1,0,3,2] row_mask:0xf bank_mask:0xf
	v_cndmask_b32_dpp v201, v114, v200, vcc quad_perm:[1,0,3,2] row_mask:0xf bank_mask:0xf
	v_cndmask_b32_e32 v118, v201, v118, vcc
	v_cndmask_b32_e32 v114, v114, v201, vcc
	v_mov_b32_dpp v200, v119 quad_perm:[1,0,3,2] row_mask:0xf bank_mask:0xf
	v_cndmask_b32_dpp v201, v115, v200, vcc quad_perm:[1,0,3,2] row_mask:0xf bank_mask:0xf
	v_cndmask_b32_e32 v119, v201, v119, vcc
	v_cndmask_b32_e32 v115, v115, v201, vcc
	v_mov_b32_dpp v200, v120 quad_perm:[1,0,3,2] row_mask:0xf bank_mask:0xf
	v_cndmask_b32_dpp v201, v116, v200, vcc quad_perm:[1,0,3,2] row_mask:0xf bank_mask:0xf
	v_cndmask_b32_e32 v120, v201, v120, vcc
	v_cndmask_b32_e32 v116, v116, v201, vcc
	v_mov_b32_dpp v200, v121 quad_perm:[1,0,3,2] row_mask:0xf bank_mask:0xf
	v_cndmask_b32_dpp v201, v117, v200, vcc quad_perm:[1,0,3,2] row_mask:0xf bank_mask:0xf
	v_cndmask_b32_e32 v121, v201, v121, vcc
	v_cndmask_b32_e32 v117, v117, v201, vcc
	v_mov_b32_dpp v200, v126 quad_perm:[1,0,3,2] row_mask:0xf bank_mask:0xf
	v_cndmask_b32_dpp v201, v122, v200, vcc quad_perm:[1,0,3,2] row_mask:0xf bank_mask:0xf
	v_cndmask_b32_e32 v126, v201, v126, vcc
	v_cndmask_b32_e32 v122, v122, v201, vcc
	v_mov_b32_dpp v200, v127 quad_perm:[1,0,3,2] row_mask:0xf bank_mask:0xf
	v_cndmask_b32_dpp v201, v123, v200, vcc quad_perm:[1,0,3,2] row_mask:0xf bank_mask:0xf
	v_cndmask_b32_e32 v127, v201, v127, vcc
	v_cndmask_b32_e32 v123, v123, v201, vcc
	v_mov_b32_dpp v200, v128 quad_perm:[1,0,3,2] row_mask:0xf bank_mask:0xf
	v_cndmask_b32_dpp v201, v124, v200, vcc quad_perm:[1,0,3,2] row_mask:0xf bank_mask:0xf
	v_cndmask_b32_e32 v128, v201, v128, vcc
	v_cndmask_b32_e32 v124, v124, v201, vcc
	v_mov_b32_dpp v200, v129 quad_perm:[1,0,3,2] row_mask:0xf bank_mask:0xf
	v_cndmask_b32_dpp v201, v125, v200, vcc quad_perm:[1,0,3,2] row_mask:0xf bank_mask:0xf
	v_cndmask_b32_e32 v129, v201, v129, vcc
	v_cndmask_b32_e32 v125, v125, v201, vcc
	s_waitcnt vmcnt(12)
	v_pk_add_f32 v[168:169], v[118:119], v[168:169]
	v_pk_add_f32 v[170:171], v[120:121], v[170:171]
	v_pk_add_f32 v[172:173], v[114:115], v[172:173]
	v_pk_add_f32 v[174:175], v[116:117], v[174:175]
	v_pk_add_f32 v[176:177], v[126:127], v[176:177]
	v_pk_add_f32 v[178:179], v[128:129], v[178:179]
	v_pk_add_f32 v[180:181], v[122:123], v[180:181]
	v_pk_add_f32 v[182:183], v[124:125], v[182:183]
	global_store_dwordx4 v[138:139], v[168:171], off sc1
	global_store_dwordx4 v[140:141], v[172:175], off sc1
	global_store_dwordx4 v[138:139], v[176:179], off offset:512 sc1
	global_store_dwordx4 v[140:141], v[180:183], off offset:512 sc1
	s_nop 1
	s_mov_b64 s[4:5], 0x80000
	v_lshl_add_u64 v[138:139], v[132:133], 0, s[4:5]
	v_lshl_add_u64 v[140:141], v[136:137], 0, s[4:5]
	global_load_dwordx4 v[168:171], v[138:139], off
	global_load_dwordx4 v[172:175], v[140:141], off
	global_load_dwordx4 v[176:179], v[138:139], off offset:512
	global_load_dwordx4 v[180:183], v[140:141], off offset:512
	v_mov_b32_dpp v200, v102 quad_perm:[1,0,3,2] row_mask:0xf bank_mask:0xf
	v_cndmask_b32_dpp v201, v98, v200, vcc quad_perm:[1,0,3,2] row_mask:0xf bank_mask:0xf
	v_cndmask_b32_e32 v102, v201, v102, vcc
	v_cndmask_b32_e32 v98, v98, v201, vcc
	v_mov_b32_dpp v200, v103 quad_perm:[1,0,3,2] row_mask:0xf bank_mask:0xf
	v_cndmask_b32_dpp v201, v99, v200, vcc quad_perm:[1,0,3,2] row_mask:0xf bank_mask:0xf
	v_cndmask_b32_e32 v103, v201, v103, vcc
	v_cndmask_b32_e32 v99, v99, v201, vcc
	v_mov_b32_dpp v200, v104 quad_perm:[1,0,3,2] row_mask:0xf bank_mask:0xf
	v_cndmask_b32_dpp v201, v100, v200, vcc quad_perm:[1,0,3,2] row_mask:0xf bank_mask:0xf
	v_cndmask_b32_e32 v104, v201, v104, vcc
	v_cndmask_b32_e32 v100, v100, v201, vcc
	v_mov_b32_dpp v200, v105 quad_perm:[1,0,3,2] row_mask:0xf bank_mask:0xf
	v_cndmask_b32_dpp v201, v101, v200, vcc quad_perm:[1,0,3,2] row_mask:0xf bank_mask:0xf
	v_cndmask_b32_e32 v105, v201, v105, vcc
	v_cndmask_b32_e32 v101, v101, v201, vcc
	v_mov_b32_dpp v200, v110 quad_perm:[1,0,3,2] row_mask:0xf bank_mask:0xf
	v_cndmask_b32_dpp v201, v106, v200, vcc quad_perm:[1,0,3,2] row_mask:0xf bank_mask:0xf
	v_cndmask_b32_e32 v110, v201, v110, vcc
	v_cndmask_b32_e32 v106, v106, v201, vcc
	v_mov_b32_dpp v200, v111 quad_perm:[1,0,3,2] row_mask:0xf bank_mask:0xf
	v_cndmask_b32_dpp v201, v107, v200, vcc quad_perm:[1,0,3,2] row_mask:0xf bank_mask:0xf
	v_cndmask_b32_e32 v111, v201, v111, vcc
	v_cndmask_b32_e32 v107, v107, v201, vcc
	v_mov_b32_dpp v200, v112 quad_perm:[1,0,3,2] row_mask:0xf bank_mask:0xf
	v_cndmask_b32_dpp v201, v108, v200, vcc quad_perm:[1,0,3,2] row_mask:0xf bank_mask:0xf
	v_cndmask_b32_e32 v112, v201, v112, vcc
	v_cndmask_b32_e32 v108, v108, v201, vcc
	v_mov_b32_dpp v200, v113 quad_perm:[1,0,3,2] row_mask:0xf bank_mask:0xf
	v_cndmask_b32_dpp v201, v109, v200, vcc quad_perm:[1,0,3,2] row_mask:0xf bank_mask:0xf
	v_cndmask_b32_e32 v113, v201, v113, vcc
	v_cndmask_b32_e32 v109, v109, v201, vcc
	s_waitcnt vmcnt(16)
;     ...
; #pragma unroll
;     for (int ai = 0; ai < 2; ++ai)
; #pragma unroll
;       for (int m = 0; m < 4; ++m)
;         epi(brow + ai * HALF + wr * 64 + m * 16 + fr, bcol + wc * 32, fq, acc[ai][0][m][0], acc[ai][0][m][1], acc[ai][1][m][0], acc[ai][1][m][1]);
	v_pk_add_f32 v[184:185], v[102:103], v[184:185]
	v_pk_add_f32 v[186:187], v[104:105], v[186:187]
	v_pk_add_f32 v[188:189], v[98:99], v[188:189]
	v_pk_add_f32 v[190:191], v[100:101], v[190:191]
	v_pk_add_f32 v[192:193], v[110:111], v[192:193]
	v_pk_add_f32 v[194:195], v[112:113], v[194:195]
	v_pk_add_f32 v[196:197], v[106:107], v[196:197]
	v_pk_add_f32 v[198:199], v[108:109], v[198:199]
	global_store_dwordx4 v[142:143], v[184:187], off sc1
	global_store_dwordx4 v[144:145], v[188:191], off sc1
	global_store_dwordx4 v[142:143], v[192:195], off offset:512 sc1
	global_store_dwordx4 v[144:145], v[196:199], off offset:512 sc1
	s_nop 1
	s_mov_b64 s[4:5], 0x90000
	v_lshl_add_u64 v[142:143], v[132:133], 0, s[4:5]
	v_lshl_add_u64 v[144:145], v[136:137], 0, s[4:5]
	global_load_dwordx4 v[184:187], v[142:143], off
	global_load_dwordx4 v[188:191], v[144:145], off
	global_load_dwordx4 v[192:195], v[142:143], off offset:512
	global_load_dwordx4 v[196:199], v[144:145], off offset:512
	v_mov_b32_dpp v200, v86 quad_perm:[1,0,3,2] row_mask:0xf bank_mask:0xf
	v_cndmask_b32_dpp v201, v82, v200, vcc quad_perm:[1,0,3,2] row_mask:0xf bank_mask:0xf
	v_cndmask_b32_e32 v86, v201, v86, vcc
	v_cndmask_b32_e32 v82, v82, v201, vcc
	v_mov_b32_dpp v200, v87 quad_perm:[1,0,3,2] row_mask:0xf bank_mask:0xf
	v_cndmask_b32_dpp v201, v83, v200, vcc quad_perm:[1,0,3,2] row_mask:0xf bank_mask:0xf
	v_cndmask_b32_e32 v87, v201, v87, vcc
	v_cndmask_b32_e32 v83, v83, v201, vcc
	v_mov_b32_dpp v200, v88 quad_perm:[1,0,3,2] row_mask:0xf bank_mask:0xf
	v_cndmask_b32_dpp v201, v84, v200, vcc quad_perm:[1,0,3,2] row_mask:0xf bank_mask:0xf
	v_cndmask_b32_e32 v88, v201, v88, vcc
	v_cndmask_b32_e32 v84, v84, v201, vcc
	v_mov_b32_dpp v200, v89 quad_perm:[1,0,3,2] row_mask:0xf bank_mask:0xf
	v_cndmask_b32_dpp v201, v85, v200, vcc quad_perm:[1,0,3,2] row_mask:0xf bank_mask:0xf
	v_cndmask_b32_e32 v89, v201, v89, vcc
	v_cndmask_b32_e32 v85, v85, v201, vcc
	v_mov_b32_dpp v200, v94 quad_perm:[1,0,3,2] row_mask:0xf bank_mask:0xf
	v_cndmask_b32_dpp v201, v90, v200, vcc quad_perm:[1,0,3,2] row_mask:0xf bank_mask:0xf
	v_cndmask_b32_e32 v94, v201, v94, vcc
	v_cndmask_b32_e32 v90, v90, v201, vcc
	v_mov_b32_dpp v200, v95 quad_perm:[1,0,3,2] row_mask:0xf bank_mask:0xf
	v_cndmask_b32_dpp v201, v91, v200, vcc quad_perm:[1,0,3,2] row_mask:0xf bank_mask:0xf
	v_cndmask_b32_e32 v95, v201, v95, vcc
	v_cndmask_b32_e32 v91, v91, v201, vcc
	v_mov_b32_dpp v200, v96 quad_perm:[1,0,3,2] row_mask:0xf bank_mask:0xf
	v_cndmask_b32_dpp v201, v92, v200, vcc quad_perm:[1,0,3,2] row_mask:0xf bank_mask:0xf
	v_cndmask_b32_e32 v96, v201, v96, vcc
	v_cndmask_b32_e32 v92, v92, v201, vcc
	v_mov_b32_dpp v200, v97 quad_perm:[1,0,3,2] row_mask:0xf bank_mask:0xf
	v_cndmask_b32_dpp v201, v93, v200, vcc quad_perm:[1,0,3,2] row_mask:0xf bank_mask:0xf
	v_cndmask_b32_e32 v97, v201, v97, vcc
	v_cndmask_b32_e32 v93, v93, v201, vcc
	s_waitcnt vmcnt(20)
	v_pk_add_f32 v[220:221], v[86:87], v[220:221]
	v_pk_add_f32 v[222:223], v[88:89], v[222:223]
	v_pk_add_f32 v[224:225], v[82:83], v[224:225]
	v_pk_add_f32 v[226:227], v[84:85], v[226:227]
	v_pk_add_f32 v[228:229], v[94:95], v[228:229]
	v_pk_add_f32 v[230:231], v[96:97], v[230:231]
	v_pk_add_f32 v[232:233], v[90:91], v[232:233]
	v_pk_add_f32 v[234:235], v[92:93], v[234:235]
	global_store_dwordx4 v[146:147], v[220:223], off sc1
	global_store_dwordx4 v[148:149], v[224:227], off sc1
	global_store_dwordx4 v[146:147], v[228:231], off offset:512 sc1
	global_store_dwordx4 v[148:149], v[232:235], off offset:512 sc1
	s_nop 1
	s_mov_b64 s[4:5], 0xa0000
	v_lshl_add_u64 v[146:147], v[132:133], 0, s[4:5]
	v_lshl_add_u64 v[148:149], v[136:137], 0, s[4:5]
	global_load_dwordx4 v[220:223], v[146:147], off
	global_load_dwordx4 v[224:227], v[148:149], off
	global_load_dwordx4 v[228:231], v[146:147], off offset:512
	global_load_dwordx4 v[232:235], v[148:149], off offset:512
	v_mov_b32_dpp v200, v70 quad_perm:[1,0,3,2] row_mask:0xf bank_mask:0xf
	v_cndmask_b32_dpp v201, v66, v200, vcc quad_perm:[1,0,3,2] row_mask:0xf bank_mask:0xf
	v_cndmask_b32_e32 v70, v201, v70, vcc
	v_cndmask_b32_e32 v66, v66, v201, vcc
	v_mov_b32_dpp v200, v71 quad_perm:[1,0,3,2] row_mask:0xf bank_mask:0xf
	v_cndmask_b32_dpp v201, v67, v200, vcc quad_perm:[1,0,3,2] row_mask:0xf bank_mask:0xf
	v_cndmask_b32_e32 v71, v201, v71, vcc
	v_cndmask_b32_e32 v67, v67, v201, vcc
	v_mov_b32_dpp v200, v72 quad_perm:[1,0,3,2] row_mask:0xf bank_mask:0xf
	v_cndmask_b32_dpp v201, v68, v200, vcc quad_perm:[1,0,3,2] row_mask:0xf bank_mask:0xf
	v_cndmask_b32_e32 v72, v201, v72, vcc
	v_cndmask_b32_e32 v68, v68, v201, vcc
	v_mov_b32_dpp v200, v73 quad_perm:[1,0,3,2] row_mask:0xf bank_mask:0xf
	v_cndmask_b32_dpp v201, v69, v200, vcc quad_perm:[1,0,3,2] row_mask:0xf bank_mask:0xf
	v_cndmask_b32_e32 v73, v201, v73, vcc
	v_cndmask_b32_e32 v69, v69, v201, vcc
	v_mov_b32_dpp v200, v78 quad_perm:[1,0,3,2] row_mask:0xf bank_mask:0xf
	v_cndmask_b32_dpp v201, v74, v200, vcc quad_perm:[1,0,3,2] row_mask:0xf bank_mask:0xf
	v_cndmask_b32_e32 v78, v201, v78, vcc
	v_cndmask_b32_e32 v74, v74, v201, vcc
	v_mov_b32_dpp v200, v79 quad_perm:[1,0,3,2] row_mask:0xf bank_mask:0xf
	v_cndmask_b32_dpp v201, v75, v200, vcc quad_perm:[1,0,3,2] row_mask:0xf bank_mask:0xf
	v_cndmask_b32_e32 v79, v201, v79, vcc
	v_cndmask_b32_e32 v75, v75, v201, vcc
	v_mov_b32_dpp v200, v80 quad_perm:[1,0,3,2] row_mask:0xf bank_mask:0xf
	v_cndmask_b32_dpp v201, v76, v200, vcc quad_perm:[1,0,3,2] row_mask:0xf bank_mask:0xf
	v_cndmask_b32_e32 v80, v201, v80, vcc
	v_cndmask_b32_e32 v76, v76, v201, vcc
	v_mov_b32_dpp v200, v81 quad_perm:[1,0,3,2] row_mask:0xf bank_mask:0xf
	v_cndmask_b32_dpp v201, v77, v200, vcc quad_perm:[1,0,3,2] row_mask:0xf bank_mask:0xf
	v_cndmask_b32_e32 v81, v201, v81, vcc
	v_cndmask_b32_e32 v77, v77, v201, vcc
	s_waitcnt vmcnt(24)
;     ...
; #pragma unroll
;     for (int ai = 0; ai < 2; ++ai)
; #pragma unroll
;       for (int m = 0; m < 4; ++m)
;         epi(brow + ai * HALF + wr * 64 + m * 16 + fr, bcol + wc * 32, fq, acc[ai][0][m][0], acc[ai][0][m][1], acc[ai][1][m][0], acc[ai][1][m][1]);
	v_pk_add_f32 v[236:237], v[70:71], v[236:237]
	v_pk_add_f32 v[238:239], v[72:73], v[238:239]
	v_pk_add_f32 v[240:241], v[66:67], v[240:241]
	v_pk_add_f32 v[242:243], v[68:69], v[242:243]
	v_pk_add_f32 v[244:245], v[78:79], v[244:245]
	v_pk_add_f32 v[246:247], v[80:81], v[246:247]
	v_pk_add_f32 v[248:249], v[74:75], v[248:249]
	v_pk_add_f32 v[250:251], v[76:77], v[250:251]
	global_store_dwordx4 v[150:151], v[236:239], off sc1
	global_store_dwordx4 v[152:153], v[240:243], off sc1
	global_store_dwordx4 v[150:151], v[244:247], off offset:512 sc1
	global_store_dwordx4 v[152:153], v[248:251], off offset:512 sc1
	s_nop 1
	s_mov_b64 s[4:5], 0xb0000
	v_lshl_add_u64 v[150:151], v[132:133], 0, s[4:5]
	v_lshl_add_u64 v[152:153], v[136:137], 0, s[4:5]
	global_load_dwordx4 v[236:239], v[150:151], off
	global_load_dwordx4 v[240:243], v[152:153], off
	global_load_dwordx4 v[244:247], v[150:151], off offset:512
	global_load_dwordx4 v[248:251], v[152:153], off offset:512
	v_mov_b32_dpp v200, v54 quad_perm:[1,0,3,2] row_mask:0xf bank_mask:0xf
	v_cndmask_b32_dpp v201, v50, v200, vcc quad_perm:[1,0,3,2] row_mask:0xf bank_mask:0xf
	v_cndmask_b32_e32 v54, v201, v54, vcc
	v_cndmask_b32_e32 v50, v50, v201, vcc
	v_mov_b32_dpp v200, v55 quad_perm:[1,0,3,2] row_mask:0xf bank_mask:0xf
	v_cndmask_b32_dpp v201, v51, v200, vcc quad_perm:[1,0,3,2] row_mask:0xf bank_mask:0xf
	v_cndmask_b32_e32 v55, v201, v55, vcc
	v_cndmask_b32_e32 v51, v51, v201, vcc
	v_mov_b32_dpp v200, v56 quad_perm:[1,0,3,2] row_mask:0xf bank_mask:0xf
	v_cndmask_b32_dpp v201, v52, v200, vcc quad_perm:[1,0,3,2] row_mask:0xf bank_mask:0xf
	v_cndmask_b32_e32 v56, v201, v56, vcc
	v_cndmask_b32_e32 v52, v52, v201, vcc
	v_mov_b32_dpp v200, v57 quad_perm:[1,0,3,2] row_mask:0xf bank_mask:0xf
	v_cndmask_b32_dpp v201, v53, v200, vcc quad_perm:[1,0,3,2] row_mask:0xf bank_mask:0xf
	v_cndmask_b32_e32 v57, v201, v57, vcc
	v_cndmask_b32_e32 v53, v53, v201, vcc
	v_mov_b32_dpp v200, v62 quad_perm:[1,0,3,2] row_mask:0xf bank_mask:0xf
	v_cndmask_b32_dpp v201, v58, v200, vcc quad_perm:[1,0,3,2] row_mask:0xf bank_mask:0xf
	v_cndmask_b32_e32 v62, v201, v62, vcc
	v_cndmask_b32_e32 v58, v58, v201, vcc
	v_mov_b32_dpp v200, v63 quad_perm:[1,0,3,2] row_mask:0xf bank_mask:0xf
	v_cndmask_b32_dpp v201, v59, v200, vcc quad_perm:[1,0,3,2] row_mask:0xf bank_mask:0xf
	v_cndmask_b32_e32 v63, v201, v63, vcc
	v_cndmask_b32_e32 v59, v59, v201, vcc
	v_mov_b32_dpp v200, v64 quad_perm:[1,0,3,2] row_mask:0xf bank_mask:0xf
	v_cndmask_b32_dpp v201, v60, v200, vcc quad_perm:[1,0,3,2] row_mask:0xf bank_mask:0xf
	v_cndmask_b32_e32 v64, v201, v64, vcc
	v_cndmask_b32_e32 v60, v60, v201, vcc
	v_mov_b32_dpp v200, v65 quad_perm:[1,0,3,2] row_mask:0xf bank_mask:0xf
	v_cndmask_b32_dpp v201, v61, v200, vcc quad_perm:[1,0,3,2] row_mask:0xf bank_mask:0xf
	v_cndmask_b32_e32 v65, v201, v65, vcc
	v_cndmask_b32_e32 v61, v61, v201, vcc
	s_waitcnt vmcnt(24)
	v_pk_add_f32 v[168:169], v[54:55], v[168:169]
	v_pk_add_f32 v[170:171], v[56:57], v[170:171]
	v_pk_add_f32 v[172:173], v[50:51], v[172:173]
	v_pk_add_f32 v[174:175], v[52:53], v[174:175]
	v_pk_add_f32 v[176:177], v[62:63], v[176:177]
	v_pk_add_f32 v[178:179], v[64:65], v[178:179]
	v_pk_add_f32 v[180:181], v[58:59], v[180:181]
	v_pk_add_f32 v[182:183], v[60:61], v[182:183]
	global_store_dwordx4 v[138:139], v[168:171], off sc1
	global_store_dwordx4 v[140:141], v[172:175], off sc1
	global_store_dwordx4 v[138:139], v[176:179], off offset:512 sc1
	global_store_dwordx4 v[140:141], v[180:183], off offset:512 sc1
	v_mov_b32_dpp v200, v38 quad_perm:[1,0,3,2] row_mask:0xf bank_mask:0xf
	v_cndmask_b32_dpp v201, v34, v200, vcc quad_perm:[1,0,3,2] row_mask:0xf bank_mask:0xf
	v_cndmask_b32_e32 v38, v201, v38, vcc
	v_cndmask_b32_e32 v34, v34, v201, vcc
	v_mov_b32_dpp v200, v39 quad_perm:[1,0,3,2] row_mask:0xf bank_mask:0xf
	v_cndmask_b32_dpp v201, v35, v200, vcc quad_perm:[1,0,3,2] row_mask:0xf bank_mask:0xf
	v_cndmask_b32_e32 v39, v201, v39, vcc
	v_cndmask_b32_e32 v35, v35, v201, vcc
	v_mov_b32_dpp v200, v40 quad_perm:[1,0,3,2] row_mask:0xf bank_mask:0xf
	v_cndmask_b32_dpp v201, v36, v200, vcc quad_perm:[1,0,3,2] row_mask:0xf bank_mask:0xf
	v_cndmask_b32_e32 v40, v201, v40, vcc
	v_cndmask_b32_e32 v36, v36, v201, vcc
	v_mov_b32_dpp v200, v41 quad_perm:[1,0,3,2] row_mask:0xf bank_mask:0xf
	v_cndmask_b32_dpp v201, v37, v200, vcc quad_perm:[1,0,3,2] row_mask:0xf bank_mask:0xf
	v_cndmask_b32_e32 v41, v201, v41, vcc
	v_cndmask_b32_e32 v37, v37, v201, vcc
	v_mov_b32_dpp v200, v46 quad_perm:[1,0,3,2] row_mask:0xf bank_mask:0xf
	v_cndmask_b32_dpp v201, v42, v200, vcc quad_perm:[1,0,3,2] row_mask:0xf bank_mask:0xf
	v_cndmask_b32_e32 v46, v201, v46, vcc
	v_cndmask_b32_e32 v42, v42, v201, vcc
	v_mov_b32_dpp v200, v47 quad_perm:[1,0,3,2] row_mask:0xf bank_mask:0xf
	v_cndmask_b32_dpp v201, v43, v200, vcc quad_perm:[1,0,3,2] row_mask:0xf bank_mask:0xf
	v_cndmask_b32_e32 v47, v201, v47, vcc
	v_cndmask_b32_e32 v43, v43, v201, vcc
	v_mov_b32_dpp v200, v48 quad_perm:[1,0,3,2] row_mask:0xf bank_mask:0xf
	v_cndmask_b32_dpp v201, v44, v200, vcc quad_perm:[1,0,3,2] row_mask:0xf bank_mask:0xf
	v_cndmask_b32_e32 v48, v201, v48, vcc
	v_cndmask_b32_e32 v44, v44, v201, vcc
	v_mov_b32_dpp v200, v49 quad_perm:[1,0,3,2] row_mask:0xf bank_mask:0xf
	v_cndmask_b32_dpp v201, v45, v200, vcc quad_perm:[1,0,3,2] row_mask:0xf bank_mask:0xf
	v_cndmask_b32_e32 v49, v201, v49, vcc
	v_cndmask_b32_e32 v45, v45, v201, vcc
	s_waitcnt vmcnt(20)
; #define WAIT_V(n) asm volatile("s_waitcnt vmcnt(" #n ")" ::: "memory")
;     ...
; #pragma unroll
;     for (int ai = 0; ai < 2; ++ai)
; #pragma unroll
;       for (int m = 0; m < 4; ++m)
;         epi(brow + ai * HALF + wr * 64 + m * 16 + fr, bcol + wc * 32, fq, acc[ai][0][m][0], acc[ai][0][m][1], acc[ai][1][m][0], acc[ai][1][m][1]);
;     ...
;   if (!have_next) { WAIT_V(0); __syncthreads(); }
	v_pk_add_f32 v[184:185], v[38:39], v[184:185]
	v_pk_add_f32 v[186:187], v[40:41], v[186:187]
	v_pk_add_f32 v[188:189], v[34:35], v[188:189]
	v_pk_add_f32 v[190:191], v[36:37], v[190:191]
	v_pk_add_f32 v[192:193], v[46:47], v[192:193]
	v_pk_add_f32 v[194:195], v[48:49], v[194:195]
	v_pk_add_f32 v[196:197], v[42:43], v[196:197]
	v_pk_add_f32 v[198:199], v[44:45], v[198:199]
	global_store_dwordx4 v[142:143], v[184:187], off sc1
	global_store_dwordx4 v[144:145], v[188:191], off sc1
	global_store_dwordx4 v[142:143], v[192:195], off offset:512 sc1
	global_store_dwordx4 v[144:145], v[196:199], off offset:512 sc1
	v_mov_b32_dpp v200, v22 quad_perm:[1,0,3,2] row_mask:0xf bank_mask:0xf
	v_cndmask_b32_dpp v201, v18, v200, vcc quad_perm:[1,0,3,2] row_mask:0xf bank_mask:0xf
	v_cndmask_b32_e32 v22, v201, v22, vcc
	v_cndmask_b32_e32 v18, v18, v201, vcc
	v_mov_b32_dpp v200, v23 quad_perm:[1,0,3,2] row_mask:0xf bank_mask:0xf
	v_cndmask_b32_dpp v201, v19, v200, vcc quad_perm:[1,0,3,2] row_mask:0xf bank_mask:0xf
	v_cndmask_b32_e32 v23, v201, v23, vcc
	v_cndmask_b32_e32 v19, v19, v201, vcc
	v_mov_b32_dpp v200, v24 quad_perm:[1,0,3,2] row_mask:0xf bank_mask:0xf
	v_cndmask_b32_dpp v201, v20, v200, vcc quad_perm:[1,0,3,2] row_mask:0xf bank_mask:0xf
	v_cndmask_b32_e32 v24, v201, v24, vcc
	v_cndmask_b32_e32 v20, v20, v201, vcc
	v_mov_b32_dpp v200, v25 quad_perm:[1,0,3,2] row_mask:0xf bank_mask:0xf
	v_cndmask_b32_dpp v201, v21, v200, vcc quad_perm:[1,0,3,2] row_mask:0xf bank_mask:0xf
	v_cndmask_b32_e32 v25, v201, v25, vcc
	v_cndmask_b32_e32 v21, v21, v201, vcc
	v_mov_b32_dpp v200, v30 quad_perm:[1,0,3,2] row_mask:0xf bank_mask:0xf
	v_cndmask_b32_dpp v201, v26, v200, vcc quad_perm:[1,0,3,2] row_mask:0xf bank_mask:0xf
	v_cndmask_b32_e32 v30, v201, v30, vcc
	v_cndmask_b32_e32 v26, v26, v201, vcc
	v_mov_b32_dpp v200, v31 quad_perm:[1,0,3,2] row_mask:0xf bank_mask:0xf
	v_cndmask_b32_dpp v201, v27, v200, vcc quad_perm:[1,0,3,2] row_mask:0xf bank_mask:0xf
	v_cndmask_b32_e32 v31, v201, v31, vcc
	v_cndmask_b32_e32 v27, v27, v201, vcc
	v_mov_b32_dpp v200, v32 quad_perm:[1,0,3,2] row_mask:0xf bank_mask:0xf
	v_cndmask_b32_dpp v201, v28, v200, vcc quad_perm:[1,0,3,2] row_mask:0xf bank_mask:0xf
	v_cndmask_b32_e32 v32, v201, v32, vcc
	v_cndmask_b32_e32 v28, v28, v201, vcc
	v_mov_b32_dpp v200, v33 quad_perm:[1,0,3,2] row_mask:0xf bank_mask:0xf
	v_cndmask_b32_dpp v201, v29, v200, vcc quad_perm:[1,0,3,2] row_mask:0xf bank_mask:0xf
	v_cndmask_b32_e32 v33, v201, v33, vcc
	v_cndmask_b32_e32 v29, v29, v201, vcc
	s_waitcnt vmcnt(16)
	v_pk_add_f32 v[220:221], v[22:23], v[220:221]
	v_pk_add_f32 v[222:223], v[24:25], v[222:223]
	v_pk_add_f32 v[224:225], v[18:19], v[224:225]
	v_pk_add_f32 v[226:227], v[20:21], v[226:227]
	v_pk_add_f32 v[228:229], v[30:31], v[228:229]
	v_pk_add_f32 v[230:231], v[32:33], v[230:231]
	v_pk_add_f32 v[232:233], v[26:27], v[232:233]
	v_pk_add_f32 v[234:235], v[28:29], v[234:235]
	global_store_dwordx4 v[146:147], v[220:223], off sc1
	global_store_dwordx4 v[148:149], v[224:227], off sc1
	global_store_dwordx4 v[146:147], v[228:231], off offset:512 sc1
	global_store_dwordx4 v[148:149], v[232:235], off offset:512 sc1
	v_mov_b32_dpp v200, v14 quad_perm:[1,0,3,2] row_mask:0xf bank_mask:0xf
	v_cndmask_b32_dpp v201, v6, v200, vcc quad_perm:[1,0,3,2] row_mask:0xf bank_mask:0xf
	v_cndmask_b32_e32 v14, v201, v14, vcc
	v_cndmask_b32_e32 v6, v6, v201, vcc
	v_mov_b32_dpp v200, v15 quad_perm:[1,0,3,2] row_mask:0xf bank_mask:0xf
	v_cndmask_b32_dpp v201, v7, v200, vcc quad_perm:[1,0,3,2] row_mask:0xf bank_mask:0xf
	v_cndmask_b32_e32 v15, v201, v15, vcc
	v_cndmask_b32_e32 v7, v7, v201, vcc
	v_mov_b32_dpp v200, v16 quad_perm:[1,0,3,2] row_mask:0xf bank_mask:0xf
	v_cndmask_b32_dpp v201, v8, v200, vcc quad_perm:[1,0,3,2] row_mask:0xf bank_mask:0xf
	v_cndmask_b32_e32 v16, v201, v16, vcc
	v_cndmask_b32_e32 v8, v8, v201, vcc
	v_mov_b32_dpp v200, v17 quad_perm:[1,0,3,2] row_mask:0xf bank_mask:0xf
	v_cndmask_b32_dpp v201, v9, v200, vcc quad_perm:[1,0,3,2] row_mask:0xf bank_mask:0xf
	v_cndmask_b32_e32 v17, v201, v17, vcc
	v_cndmask_b32_e32 v9, v9, v201, vcc
	v_mov_b32_dpp v200, v10 quad_perm:[1,0,3,2] row_mask:0xf bank_mask:0xf
	v_cndmask_b32_dpp v201, v2, v200, vcc quad_perm:[1,0,3,2] row_mask:0xf bank_mask:0xf
	v_cndmask_b32_e32 v10, v201, v10, vcc
	v_cndmask_b32_e32 v2, v2, v201, vcc
	v_mov_b32_dpp v200, v11 quad_perm:[1,0,3,2] row_mask:0xf bank_mask:0xf
	v_cndmask_b32_dpp v201, v3, v200, vcc quad_perm:[1,0,3,2] row_mask:0xf bank_mask:0xf
	v_cndmask_b32_e32 v11, v201, v11, vcc
	v_cndmask_b32_e32 v3, v3, v201, vcc
	v_mov_b32_dpp v200, v12 quad_perm:[1,0,3,2] row_mask:0xf bank_mask:0xf
	v_cndmask_b32_dpp v201, v4, v200, vcc quad_perm:[1,0,3,2] row_mask:0xf bank_mask:0xf
	v_cndmask_b32_e32 v12, v201, v12, vcc
	v_cndmask_b32_e32 v4, v4, v201, vcc
	v_mov_b32_dpp v200, v13 quad_perm:[1,0,3,2] row_mask:0xf bank_mask:0xf
	v_cndmask_b32_dpp v201, v5, v200, vcc quad_perm:[1,0,3,2] row_mask:0xf bank_mask:0xf
	v_cndmask_b32_e32 v13, v201, v13, vcc
	v_cndmask_b32_e32 v5, v5, v201, vcc
	s_waitcnt vmcnt(12)
	v_pk_add_f32 v[236:237], v[14:15], v[236:237]
	v_pk_add_f32 v[238:239], v[16:17], v[238:239]
	v_pk_add_f32 v[240:241], v[6:7], v[240:241]
	v_pk_add_f32 v[242:243], v[8:9], v[242:243]
	v_pk_add_f32 v[244:245], v[10:11], v[244:245]
	v_pk_add_f32 v[246:247], v[12:13], v[246:247]
	v_pk_add_f32 v[248:249], v[2:3], v[248:249]
	v_pk_add_f32 v[250:251], v[4:5], v[250:251]
	global_store_dwordx4 v[150:151], v[236:239], off sc1
	global_store_dwordx4 v[152:153], v[240:243], off sc1
	global_store_dwordx4 v[150:151], v[244:247], off offset:512 sc1
	global_store_dwordx4 v[152:153], v[248:251], off offset:512 sc1
	v_cmp_ne_u32_e64 s[4:5], 1, v0
	s_andn2_b64 vcc, exec, s[2:3]
	s_cbranch_vccnz .LBB0_1551
	s_waitcnt vmcnt(0)
	s_waitcnt lgkmcnt(0)
	s_barrier
	s_branch .LBB0_1551
